# v40 + mLSTM stage C output epilogue: all hnorm/o-gate loads hoisted into fresh registers (duplicates removed), exact counted vmcnt waits so no wait covers a store
# baseline (speedup 1.0000x reference)
; __device__ __forceinline__ unsigned pk2(float lo, float hi) { return f2bf(lo) | (f2bf(hi) << 16); }
; __device__ __forceinline__ float bflo(unsigned w) { return __uint_as_float(w << 16); }
; __device__ __forceinline__ float bfhi(unsigned w) { return __uint_as_float(w & 0xffff0000u); }
; __device__ __forceinline__ float sigmoidf_(float x) { return 1.0f / (1.0f + __expf(-x)); }
; __device__ __forceinline__ void mlstm_stage_c(LAS unsigned char* lds, const bf16_t* QKO, const bf16_t* KVT, const float* G, const float* gbias, const bf16_t* DC, const float* DN, ...
;     ...
;         for (int tb = 0; tb < 2; ++tb) { const int t = tb * 32 + r32; float tot = 0.f;
; #pragma unroll
;             for (int w = 0; w < 8; ++w) tot += sSsq[w * 64 + t];
;             const float rstd = 1.0f / sqrtf(tot * (1.0f / 512.0f) + EPS);
; #pragma unroll
;             for (int vb = 0; vb < 2; ++vb)
; #pragma unroll
;                 for (int gq = 0; gq < 4; ++gq) { const int v0 = wave * 64 + vb * 32 + 8 * gq + 4 * hi;
;                     const u32x2 ow = *(const u32x2*)(QKO + (size_t)(t0 + t) * 4096 + 2048 + h * 512 + v0);
;                     const f32x4 gn = *(const f32x4*)(hnorm + h * 512 + v0);
;                     const float o0 = acc[vb][tb][4 * gq] * rstd * gn.x * sigmoidf_(bflo(ow.x)), o1 = acc[vb][tb][4 * gq + 1] * rstd * gn.y * sigmoidf_(bfhi(ow.x));
;                     const float o2 = acc[vb][tb][4 * gq + 2] * rstd * gn.z * sigmoidf_(bflo(ow.y)), o3 = acc[vb][tb][4 * gq + 3] * rstd * gn.w * sigmoidf_(bfhi(ow.y));
;                     u32x2 w; w.x = pk2(o0, o1); w.y = pk2(o2, o3);
;                     *(u32x2*)(HG + (size_t)(t0 + t) * 2048 + h * 512 + v0) = w; } }
.LBB0_781:
	s_or_b64 exec, exec, s[0:1]
	s_lshl_b32 s78, s20, 1
	s_mov_b32 s79, s21
	s_waitcnt lgkmcnt(0)
	v_lshl_add_u64 v[0:1], v[82:83], 0, s[78:79]
	v_readlane_b32 s0, v249, 50
	v_lshl_add_u64 v[82:83], v[0:1], 0, v[78:79]
	s_add_u32 s4, s0, s78
	v_add_co_u32_e32 v0, vcc, s27, v82
	v_readlane_b32 s0, v249, 51
	s_nop 0
	v_addc_co_u32_e32 v1, vcc, 0, v83, vcc
	s_addc_u32 s5, s0, 0
	s_lshl_b32 s20, s20, 2
	s_barrier
	global_load_dwordx2 v[150:151], v[0:1], off
	v_lshl_add_u64 v[4:5], v[74:75], 0, s[20:21]
	global_load_dwordx4 v[152:155], v[4:5], off
	global_load_dwordx4 v[160:163], v[4:5], off offset:32
	global_load_dwordx4 v[168:171], v[4:5], off offset:64
	global_load_dwordx4 v[172:175], v[4:5], off offset:96
	global_load_dwordx4 v[176:179], v[4:5], off offset:128
	global_load_dwordx4 v[184:187], v[4:5], off offset:160
	global_load_dwordx4 v[188:191], v[4:5], off offset:192
	global_load_dwordx4 v[192:195], v[4:5], off offset:224
	v_add_u32_e32 v42, 0xc00, v114
	v_add_u32_e32 v58, 0x1000, v114
	v_add_u32_e32 v60, 0x1400, v114
	ds_read2_b32 v[38:39], v42 offset0:64 offset1:96
	ds_read2_b32 v[40:41], v42 offset0:128 offset1:160
	ds_read2_b32 v[42:43], v42 offset0:192 offset1:224
	ds_read2_b32 v[44:45], v58 offset1:32
	ds_read2_b32 v[46:47], v58 offset0:64 offset1:96
	ds_read2_b32 v[56:57], v58 offset0:128 offset1:160
	ds_read2_b32 v[58:59], v58 offset0:192 offset1:224
	ds_read2_b32 v[60:61], v60 offset1:32
	s_waitcnt lgkmcnt(7)
	v_add_f32_e32 v38, 0, v38
	s_waitcnt lgkmcnt(6)
	v_add_f32_e32 v38, v38, v40
	s_waitcnt lgkmcnt(5)
	v_add_f32_e32 v38, v38, v42
	s_waitcnt lgkmcnt(4)
	v_add_f32_e32 v38, v38, v44
	s_waitcnt lgkmcnt(3)
	v_add_f32_e32 v38, v38, v46
	s_waitcnt lgkmcnt(2)
	v_add_f32_e32 v38, v38, v56
	s_waitcnt lgkmcnt(1)
	v_add_f32_e32 v38, v38, v58
	s_waitcnt lgkmcnt(0)
	v_add_f32_e32 v38, v38, v60
	v_fmamk_f32 v38, v38, 0x3b000000, v138
	v_mul_f32_e32 v40, 0x4f800000, v38
	v_cmp_gt_f32_e32 vcc, s26, v38
	v_mov_b32_e32 v110, v104
	v_mov_b32_e32 v111, v102
	v_cndmask_b32_e32 v38, v38, v40, vcc
	v_sqrt_f32_e32 v40, v38
	v_lshlrev_b64 v[80:81], 12, v[80:81]
	v_lshl_add_u64 v[82:83], v[82:83], 0, s[56:57]
	global_load_dwordx2 v[206:207], v[82:83], off offset:112
	global_load_dwordx2 v[156:157], v[82:83], off offset:16
	global_load_dwordx2 v[158:159], v[82:83], off offset:32
	global_load_dwordx2 v[164:165], v[82:83], off offset:48
	global_load_dwordx2 v[166:167], v[82:83], off offset:64
	global_load_dwordx2 v[180:181], v[82:83], off offset:80
	global_load_dwordx2 v[182:183], v[82:83], off offset:96
	v_lshl_add_u64 v[106:107], s[4:5], 0, v[80:81]
	v_add_u32_e32 v42, -1, v40
	v_add_u32_e32 v44, 1, v40
	v_fma_f32 v46, -v42, v40, v38
	v_fma_f32 v56, -v44, v40, v38
	v_cmp_ge_f32_e64 s[0:1], 0, v46
	v_mov_b32_e32 v102, v105
	v_cndmask_b32_e64 v40, v40, v42, s[0:1]
	v_cmp_lt_f32_e64 s[0:1], 0, v56
	v_add_u32_e32 v76, s96, v76
	s_nop 0
	v_cndmask_b32_e64 v40, v40, v44, s[0:1]
	v_mul_f32_e32 v42, 0x37800000, v40
	v_cndmask_b32_e32 v40, v40, v42, vcc
	v_cmp_class_f32_e32 vcc, v38, v139
	s_nop 1
	v_cndmask_b32_e32 v38, v40, v38, vcc
	v_div_scale_f32 v42, s[0:1], v38, v38, 1.0
	v_rcp_f32_e32 v40, v42
	v_div_scale_f32 v44, vcc, 1.0, v38, 1.0
	v_fma_f32 v46, -v42, v40, 1.0
	v_fmac_f32_e32 v40, v46, v40
	v_mul_f32_e32 v46, v44, v40
	v_fma_f32 v56, -v42, v46, v44
	v_fmac_f32_e32 v46, v56, v40
	v_fma_f32 v42, -v42, v46, v44
	v_div_fmas_f32 v40, v42, v40, v46
	v_div_fixup_f32 v38, v40, v38, 1.0
	v_pk_mul_f32 v[110:111], v[110:111], v[38:39] op_sel_hi:[1,0]
	v_pk_mul_f32 v[102:103], v[102:103], v[38:39] op_sel_hi:[1,0]
	s_waitcnt vmcnt(15)
	v_lshlrev_b32_e32 v40, 16, v150
	v_lshlrev_b32_e32 v44, 16, v151
	v_and_b32_e32 v42, 0xffff0000, v150
	v_and_b32_e32 v46, 0xffff0000, v151
	s_waitcnt vmcnt(14)
	v_mov_b32_e32 v108, v152
	v_mul_f32_e32 v0, 0xbfb8aa3b, v40
	v_mul_f32_e32 v40, 0xbfb8aa3b, v44
	v_mov_b32_e32 v109, v154
	v_mul_f32_e32 v2, 0xbfb8aa3b, v42
	v_exp_f32_e32 v144, v0
	v_exp_f32_e32 v145, v40
	v_mul_f32_e32 v0, 0xbfb8aa3b, v46
	v_pk_mul_f32 v[108:109], v[108:109], v[110:111]
	v_exp_f32_e32 v110, v2
	v_exp_f32_e32 v111, v0
	v_pk_add_f32 v[144:145], v[144:145], 1.0 op_sel_hi:[1,0]
	v_pk_add_f32 v[104:105], v[110:111], 1.0 op_sel_hi:[1,0]
	v_div_scale_f32 v2, s[0:1], v145, v145, 1.0
	v_rcp_f32_e32 v40, v2
	v_div_scale_f32 v0, vcc, 1.0, v145, 1.0
	v_fma_f32 v42, -v2, v40, 1.0
	v_fmac_f32_e32 v40, v42, v40
	v_mul_f32_e32 v42, v0, v40
	v_fma_f32 v44, -v2, v42, v0
	v_fmac_f32_e32 v42, v44, v40
	v_fma_f32 v0, -v2, v42, v0
	v_div_scale_f32 v2, s[0:1], v144, v144, 1.0
	v_rcp_f32_e32 v44, v2
	v_div_fmas_f32 v0, v0, v40, v42
	v_div_fixup_f32 v145, v0, v145, 1.0
	v_fma_f32 v0, -v2, v44, 1.0
	v_fmac_f32_e32 v44, v0, v44
	v_div_scale_f32 v0, vcc, 1.0, v144, 1.0
	v_mul_f32_e32 v40, v0, v44
	v_fma_f32 v42, -v2, v40, v0
	v_fmac_f32_e32 v40, v42, v44
	v_fma_f32 v0, -v2, v40, v0
	v_div_fmas_f32 v0, v0, v44, v40
	v_div_scale_f32 v40, s[0:1], v105, v105, 1.0
	v_rcp_f32_e32 v42, v40
	v_mov_b32_e32 v2, v153
	v_div_fixup_f32 v144, v0, v144, 1.0
	v_mov_b32_e32 v3, v155
	v_pk_mul_f32 v[0:1], v[2:3], v[102:103]
	v_fma_f32 v2, -v40, v42, 1.0
	v_fmac_f32_e32 v42, v2, v42
	v_div_scale_f32 v2, vcc, 1.0, v105, 1.0
	v_mul_f32_e32 v3, v2, v42
	v_fma_f32 v44, -v40, v3, v2
	v_fmac_f32_e32 v3, v44, v42
	v_fma_f32 v2, -v40, v3, v2
	v_div_scale_f32 v40, s[0:1], v104, v104, 1.0
	v_rcp_f32_e32 v44, v40
	v_div_fmas_f32 v2, v2, v42, v3
	v_div_fixup_f32 v3, v2, v105, 1.0
	v_pk_mul_f32 v[108:109], v[108:109], v[144:145]
	v_fma_f32 v2, -v40, v44, 1.0
	v_fmac_f32_e32 v44, v2, v44
	v_div_scale_f32 v2, vcc, 1.0, v104, 1.0
	v_mul_f32_e32 v42, v2, v44
	v_fma_f32 v46, -v40, v42, v2
	v_fmac_f32_e32 v42, v46, v44
	v_fma_f32 v2, -v40, v42, v2
	v_div_fmas_f32 v2, v2, v44, v42
	v_div_fixup_f32 v2, v2, v104, 1.0
	v_pk_mul_f32 v[0:1], v[0:1], v[2:3]
	v_and_b32_sdwa v3, v108, v142 dst_sel:DWORD dst_unused:UNUSED_PAD src0_sel:WORD_1 src1_sel:DWORD
	v_add3_u32 v40, v108, v3, s25
	v_and_b32_sdwa v3, v1, v142 dst_sel:DWORD dst_unused:UNUSED_PAD src0_sel:WORD_1 src1_sel:DWORD
	v_and_b32_sdwa v42, v0, v142 dst_sel:DWORD dst_unused:UNUSED_PAD src0_sel:WORD_1 src1_sel:DWORD
	v_and_b32_sdwa v2, v109, v142 dst_sel:DWORD dst_unused:UNUSED_PAD src0_sel:WORD_1 src1_sel:DWORD
	v_add3_u32 v1, v1, v3, s25
	v_add3_u32 v0, v0, v42, s25
	v_add3_u32 v2, v109, v2, s25
	v_and_b32_e32 v1, 0xffff0000, v1
	v_and_b32_e32 v0, 0xffff0000, v0
	v_or_b32_sdwa v3, v1, v2 dst_sel:DWORD dst_unused:UNUSED_PAD src0_sel:DWORD src1_sel:WORD_1
	v_or_b32_sdwa v2, v0, v40 dst_sel:DWORD dst_unused:UNUSED_PAD src0_sel:DWORD src1_sel:WORD_1
	v_lshl_add_u64 v[0:1], v[106:107], 0, v[78:79]
	global_store_dwordx2 v[0:1], v[2:3], off
	s_nop 0
	v_mov_b32_e32 v106, v100
	v_mov_b32_e32 v107, v98
	v_mov_b32_e32 v98, v101
	v_pk_mul_f32 v[98:99], v[98:99], v[38:39] op_sel_hi:[1,0]
	v_pk_mul_f32 v[106:107], v[106:107], v[38:39] op_sel_hi:[1,0]
	s_waitcnt vmcnt(6)
; __device__ __forceinline__ unsigned pk2(float lo, float hi) { return f2bf(lo) | (f2bf(hi) << 16); }
; __device__ __forceinline__ float bflo(unsigned w) { return __uint_as_float(w << 16); }
; __device__ __forceinline__ float bfhi(unsigned w) { return __uint_as_float(w & 0xffff0000u); }
; __device__ __forceinline__ float sigmoidf_(float x) { return 1.0f / (1.0f + __expf(-x)); }
; __device__ __forceinline__ void mlstm_stage_c(LAS unsigned char* lds, const bf16_t* QKO, const bf16_t* KVT, const float* G, const float* gbias, const bf16_t* DC, const float* DN, ...
;     ...
; #pragma unroll
;             for (int vb = 0; vb < 2; ++vb)
; #pragma unroll
;                 for (int gq = 0; gq < 4; ++gq) { const int v0 = wave * 64 + vb * 32 + 8 * gq + 4 * hi;
;                     const u32x2 ow = *(const u32x2*)(QKO + (size_t)(t0 + t) * 4096 + 2048 + h * 512 + v0);
;                     const f32x4 gn = *(const f32x4*)(hnorm + h * 512 + v0);
;                     const float o0 = acc[vb][tb][4 * gq] * rstd * gn.x * sigmoidf_(bflo(ow.x)), o1 = acc[vb][tb][4 * gq + 1] * rstd * gn.y * sigmoidf_(bfhi(ow.x));
;                     const float o2 = acc[vb][tb][4 * gq + 2] * rstd * gn.z * sigmoidf_(bflo(ow.y)), o3 = acc[vb][tb][4 * gq + 3] * rstd * gn.w * sigmoidf_(bfhi(ow.y));
;                     u32x2 w; w.x = pk2(o0, o1); w.y = pk2(o2, o3);
;                     *(u32x2*)(HG + (size_t)(t0 + t) * 2048 + h * 512 + v0) = w; } }
	v_lshlrev_b32_e32 v40, 16, v156
	v_lshlrev_b32_e32 v42, 16, v157
	v_mul_f32_e32 v40, 0xbfb8aa3b, v40
	v_mul_f32_e32 v42, 0xbfb8aa3b, v42
	v_exp_f32_e32 v146, v40
	v_exp_f32_e32 v147, v42
	v_and_b32_e32 v40, 0xffff0000, v156
	v_and_b32_e32 v42, 0xffff0000, v157
	v_mul_f32_e32 v40, 0xbfb8aa3b, v40
	v_pk_add_f32 v[110:111], v[146:147], 1.0 op_sel_hi:[1,0]
	v_exp_f32_e32 v146, v40
	v_div_scale_f32 v44, s[0:1], v111, v111, 1.0
	v_rcp_f32_e32 v46, v44
	v_mul_f32_e32 v42, 0xbfb8aa3b, v42
	v_exp_f32_e32 v147, v42
	v_fma_f32 v40, -v44, v46, 1.0
	v_fmac_f32_e32 v46, v40, v46
	v_div_scale_f32 v40, vcc, 1.0, v111, 1.0
	v_mul_f32_e32 v42, v40, v46
	v_fma_f32 v56, -v44, v42, v40
	v_fmac_f32_e32 v42, v56, v46
	v_fma_f32 v40, -v44, v42, v40
	v_div_scale_f32 v44, s[0:1], v110, v110, 1.0
	v_rcp_f32_e32 v56, v44
	v_div_fmas_f32 v40, v40, v46, v42
	v_div_fixup_f32 v111, v40, v111, 1.0
	v_pk_add_f32 v[100:101], v[146:147], 1.0 op_sel_hi:[1,0]
	v_fma_f32 v40, -v44, v56, 1.0
	v_fmac_f32_e32 v56, v40, v56
	v_div_scale_f32 v40, vcc, 1.0, v110, 1.0
	v_mul_f32_e32 v42, v40, v56
	v_fma_f32 v46, -v44, v42, v40
	v_fmac_f32_e32 v42, v46, v56
	v_fma_f32 v40, -v44, v42, v40
	v_div_fmas_f32 v40, v40, v56, v42
	v_div_fixup_f32 v110, v40, v110, 1.0
	v_div_scale_f32 v40, s[0:1], v101, v101, 1.0
	v_rcp_f32_e32 v42, v40
	v_mov_b32_e32 v149, v162
	v_fma_f32 v44, -v40, v42, 1.0
	v_fmac_f32_e32 v42, v44, v42
	v_div_scale_f32 v44, vcc, 1.0, v101, 1.0
	v_mul_f32_e32 v46, v44, v42
	v_fma_f32 v56, -v40, v46, v44
	v_fmac_f32_e32 v46, v56, v42
	v_fma_f32 v40, -v40, v46, v44
	v_div_scale_f32 v44, s[0:1], v100, v100, 1.0
	v_rcp_f32_e32 v56, v44
	v_div_fmas_f32 v40, v40, v42, v46
	v_div_fixup_f32 v101, v40, v101, 1.0
	v_mov_b32_e32 v104, v161
	v_fma_f32 v40, -v44, v56, 1.0
	v_fmac_f32_e32 v56, v40, v56
	v_div_scale_f32 v40, vcc, 1.0, v100, 1.0
	v_mul_f32_e32 v42, v40, v56
	v_fma_f32 v46, -v44, v42, v40
	v_fmac_f32_e32 v42, v46, v56
	v_fma_f32 v40, -v44, v42, v40
	v_div_fmas_f32 v40, v40, v56, v42
	v_mov_b32_e32 v148, v160
	v_mov_b32_e32 v105, v163
	v_pk_mul_f32 v[98:99], v[104:105], v[98:99]
	v_div_fixup_f32 v100, v40, v100, 1.0
	v_pk_mul_f32 v[106:107], v[148:149], v[106:107]
	v_pk_mul_f32 v[98:99], v[98:99], v[100:101]
	v_pk_mul_f32 v[106:107], v[106:107], v[110:111]
	v_and_b32_sdwa v44, v99, v142 dst_sel:DWORD dst_unused:UNUSED_PAD src0_sel:WORD_1 src1_sel:DWORD
	v_and_b32_sdwa v46, v98, v142 dst_sel:DWORD dst_unused:UNUSED_PAD src0_sel:WORD_1 src1_sel:DWORD
	v_and_b32_sdwa v40, v107, v142 dst_sel:DWORD dst_unused:UNUSED_PAD src0_sel:WORD_1 src1_sel:DWORD
	v_and_b32_sdwa v42, v106, v142 dst_sel:DWORD dst_unused:UNUSED_PAD src0_sel:WORD_1 src1_sel:DWORD
	v_add3_u32 v44, v99, v44, s25
	v_add3_u32 v46, v98, v46, s25
	v_add3_u32 v42, v106, v42, s25
	v_add3_u32 v40, v107, v40, s25
	v_and_b32_e32 v44, 0xffff0000, v44
	v_and_b32_e32 v46, 0xffff0000, v46
	v_or_b32_sdwa v99, v44, v40 dst_sel:DWORD dst_unused:UNUSED_PAD src0_sel:DWORD src1_sel:WORD_1
	v_or_b32_sdwa v98, v46, v42 dst_sel:DWORD dst_unused:UNUSED_PAD src0_sel:DWORD src1_sel:WORD_1
	global_store_dwordx2 v[0:1], v[98:99], off offset:16
	s_waitcnt vmcnt(6)
	v_lshlrev_b32_e32 v40, 16, v158
	v_mul_f32_e32 v40, 0xbfb8aa3b, v40
	v_exp_f32_e32 v102, v40
	v_and_b32_e32 v40, 0xffff0000, v158
	v_mul_f32_e32 v40, 0xbfb8aa3b, v40
	v_exp_f32_e32 v104, v40
	v_lshlrev_b32_e32 v40, 16, v159
	v_mul_f32_e32 v40, 0xbfb8aa3b, v40
	v_exp_f32_e32 v103, v40
	v_and_b32_e32 v40, 0xffff0000, v159
	v_mul_f32_e32 v40, 0xbfb8aa3b, v40
	v_exp_f32_e32 v105, v40
	v_pk_add_f32 v[102:103], v[102:103], 1.0 op_sel_hi:[1,0]
	v_mov_b32_e32 v106, v96
	v_div_scale_f32 v40, s[0:1], v103, v103, 1.0
	v_rcp_f32_e32 v42, v40
	v_mov_b32_e32 v107, v94
	v_mov_b32_e32 v94, v97
	v_pk_add_f32 v[96:97], v[104:105], 1.0 op_sel_hi:[1,0]
	v_fma_f32 v44, -v40, v42, 1.0
	v_fmac_f32_e32 v42, v44, v42
	v_div_scale_f32 v44, vcc, 1.0, v103, 1.0
	v_mul_f32_e32 v46, v44, v42
	v_fma_f32 v56, -v40, v46, v44
	v_fmac_f32_e32 v46, v56, v42
	v_fma_f32 v40, -v40, v46, v44
	v_div_scale_f32 v44, s[0:1], v102, v102, 1.0
	v_rcp_f32_e32 v56, v44
	v_div_fmas_f32 v40, v40, v42, v46
	v_div_fixup_f32 v103, v40, v103, 1.0
	v_pk_mul_f32 v[94:95], v[94:95], v[38:39] op_sel_hi:[1,0]
	v_fma_f32 v40, -v44, v56, 1.0
	v_fmac_f32_e32 v56, v40, v56
	v_div_scale_f32 v40, vcc, 1.0, v102, 1.0
	v_mul_f32_e32 v42, v40, v56
	v_fma_f32 v46, -v44, v42, v40
	v_fmac_f32_e32 v42, v46, v56
	v_fma_f32 v40, -v44, v42, v40
	v_div_fmas_f32 v40, v40, v56, v42
	v_div_fixup_f32 v102, v40, v102, 1.0
	v_div_scale_f32 v40, s[0:1], v97, v97, 1.0
	v_rcp_f32_e32 v42, v40
	v_pk_mul_f32 v[106:107], v[106:107], v[38:39] op_sel_hi:[1,0]
	v_fma_f32 v44, -v40, v42, 1.0
	v_fmac_f32_e32 v42, v44, v42
	v_div_scale_f32 v44, vcc, 1.0, v97, 1.0
	v_mul_f32_e32 v46, v44, v42
	v_fma_f32 v56, -v40, v46, v44
	v_fmac_f32_e32 v46, v56, v42
	v_fma_f32 v40, -v40, v46, v44
	v_div_scale_f32 v44, s[0:1], v96, v96, 1.0
	v_rcp_f32_e32 v56, v44
	v_div_fmas_f32 v40, v40, v42, v46
	v_div_fixup_f32 v97, v40, v97, 1.0
	v_fma_f32 v40, -v44, v56, 1.0
	v_fmac_f32_e32 v56, v40, v56
	v_div_scale_f32 v40, vcc, 1.0, v96, 1.0
	v_mul_f32_e32 v42, v40, v56
	v_fma_f32 v46, -v44, v42, v40
	v_fmac_f32_e32 v42, v46, v56
	v_fma_f32 v40, -v44, v42, v40
	v_div_fmas_f32 v40, v40, v56, v42
	v_div_fixup_f32 v96, v40, v96, 1.0
	v_mov_b32_e32 v109, v170
	v_mov_b32_e32 v100, v169
	v_mov_b32_e32 v108, v168
	v_mov_b32_e32 v101, v171
	v_pk_mul_f32 v[94:95], v[94:95], v[100:101]
	v_pk_mul_f32 v[106:107], v[106:107], v[108:109]
	v_pk_mul_f32 v[94:95], v[94:95], v[96:97]
	v_pk_mul_f32 v[102:103], v[106:107], v[102:103]
	v_and_b32_sdwa v44, v95, v142 dst_sel:DWORD dst_unused:UNUSED_PAD src0_sel:WORD_1 src1_sel:DWORD
	v_and_b32_sdwa v46, v94, v142 dst_sel:DWORD dst_unused:UNUSED_PAD src0_sel:WORD_1 src1_sel:DWORD
	v_and_b32_sdwa v40, v103, v142 dst_sel:DWORD dst_unused:UNUSED_PAD src0_sel:WORD_1 src1_sel:DWORD
	v_and_b32_sdwa v42, v102, v142 dst_sel:DWORD dst_unused:UNUSED_PAD src0_sel:WORD_1 src1_sel:DWORD
	v_add3_u32 v44, v95, v44, s25
	v_add3_u32 v46, v94, v46, s25
	v_add3_u32 v42, v102, v42, s25
	v_add3_u32 v40, v103, v40, s25
	v_and_b32_e32 v44, 0xffff0000, v44
	v_and_b32_e32 v46, 0xffff0000, v46
	v_or_b32_sdwa v95, v44, v40 dst_sel:DWORD dst_unused:UNUSED_PAD src0_sel:DWORD src1_sel:WORD_1
	v_or_b32_sdwa v94, v46, v42 dst_sel:DWORD dst_unused:UNUSED_PAD src0_sel:DWORD src1_sel:WORD_1
	global_store_dwordx2 v[0:1], v[94:95], off offset:32
	s_waitcnt vmcnt(6)
; __device__ __forceinline__ unsigned pk2(float lo, float hi) { return f2bf(lo) | (f2bf(hi) << 16); }
; __device__ __forceinline__ float bflo(unsigned w) { return __uint_as_float(w << 16); }
; __device__ __forceinline__ float bfhi(unsigned w) { return __uint_as_float(w & 0xffff0000u); }
; __device__ __forceinline__ float sigmoidf_(float x) { return 1.0f / (1.0f + __expf(-x)); }
; __device__ __forceinline__ void mlstm_stage_c(LAS unsigned char* lds, const bf16_t* QKO, const bf16_t* KVT, const float* G, const float* gbias, const bf16_t* DC, const float* DN, ...
;     ...
; #pragma unroll
;             for (int vb = 0; vb < 2; ++vb)
; #pragma unroll
;                 for (int gq = 0; gq < 4; ++gq) { const int v0 = wave * 64 + vb * 32 + 8 * gq + 4 * hi;
;                     const u32x2 ow = *(const u32x2*)(QKO + (size_t)(t0 + t) * 4096 + 2048 + h * 512 + v0);
;                     const f32x4 gn = *(const f32x4*)(hnorm + h * 512 + v0);
;                     const float o0 = acc[vb][tb][4 * gq] * rstd * gn.x * sigmoidf_(bflo(ow.x)), o1 = acc[vb][tb][4 * gq + 1] * rstd * gn.y * sigmoidf_(bfhi(ow.x));
;                     const float o2 = acc[vb][tb][4 * gq + 2] * rstd * gn.z * sigmoidf_(bflo(ow.y)), o3 = acc[vb][tb][4 * gq + 3] * rstd * gn.w * sigmoidf_(bfhi(ow.y));
;                     u32x2 w; w.x = pk2(o0, o1); w.y = pk2(o2, o3);
;                     *(u32x2*)(HG + (size_t)(t0 + t) * 2048 + h * 512 + v0) = w; } }
	v_lshlrev_b32_e32 v40, 16, v164
	v_mul_f32_e32 v40, 0xbfb8aa3b, v40
	v_exp_f32_e32 v98, v40
	v_and_b32_e32 v40, 0xffff0000, v164
	v_mul_f32_e32 v40, 0xbfb8aa3b, v40
	v_exp_f32_e32 v100, v40
	v_lshlrev_b32_e32 v40, 16, v165
	v_mul_f32_e32 v40, 0xbfb8aa3b, v40
	v_exp_f32_e32 v99, v40
	v_and_b32_e32 v40, 0xffff0000, v165
	v_mul_f32_e32 v40, 0xbfb8aa3b, v40
	v_exp_f32_e32 v101, v40
	v_pk_add_f32 v[98:99], v[98:99], 1.0 op_sel_hi:[1,0]
	v_mov_b32_e32 v102, v92
	v_div_scale_f32 v40, s[0:1], v99, v99, 1.0
	v_rcp_f32_e32 v42, v40
	v_mov_b32_e32 v103, v88
	v_mov_b32_e32 v88, v93
	v_pk_add_f32 v[92:93], v[100:101], 1.0 op_sel_hi:[1,0]
	v_fma_f32 v44, -v40, v42, 1.0
	v_fmac_f32_e32 v42, v44, v42
	v_div_scale_f32 v44, vcc, 1.0, v99, 1.0
	v_mul_f32_e32 v46, v44, v42
	v_fma_f32 v56, -v40, v46, v44
	v_fmac_f32_e32 v46, v56, v42
	v_fma_f32 v40, -v40, v46, v44
	v_div_scale_f32 v44, s[0:1], v98, v98, 1.0
	v_rcp_f32_e32 v56, v44
	v_div_fmas_f32 v40, v40, v42, v46
	v_div_fixup_f32 v99, v40, v99, 1.0
	v_pk_mul_f32 v[88:89], v[88:89], v[38:39] op_sel_hi:[1,0]
	v_fma_f32 v40, -v44, v56, 1.0
	v_fmac_f32_e32 v56, v40, v56
	v_div_scale_f32 v40, vcc, 1.0, v98, 1.0
	v_mul_f32_e32 v42, v40, v56
	v_fma_f32 v46, -v44, v42, v40
	v_fmac_f32_e32 v42, v46, v56
	v_fma_f32 v40, -v44, v42, v40
	v_div_fmas_f32 v40, v40, v56, v42
	v_div_fixup_f32 v98, v40, v98, 1.0
	v_div_scale_f32 v40, s[0:1], v93, v93, 1.0
	v_rcp_f32_e32 v42, v40
	v_pk_mul_f32 v[102:103], v[102:103], v[38:39] op_sel_hi:[1,0]
	v_fma_f32 v44, -v40, v42, 1.0
	v_fmac_f32_e32 v42, v44, v42
	v_div_scale_f32 v44, vcc, 1.0, v93, 1.0
	v_mul_f32_e32 v46, v44, v42
	v_fma_f32 v56, -v40, v46, v44
	v_fmac_f32_e32 v46, v56, v42
	v_fma_f32 v40, -v40, v46, v44
	v_div_scale_f32 v44, s[0:1], v92, v92, 1.0
	v_rcp_f32_e32 v56, v44
	v_div_fmas_f32 v40, v40, v42, v46
	v_div_fixup_f32 v93, v40, v93, 1.0
	v_fma_f32 v40, -v44, v56, 1.0
	v_fmac_f32_e32 v56, v40, v56
	v_div_scale_f32 v40, vcc, 1.0, v92, 1.0
	v_mul_f32_e32 v42, v40, v56
	v_fma_f32 v46, -v44, v42, v40
	v_fmac_f32_e32 v42, v46, v56
	v_fma_f32 v40, -v44, v42, v40
	v_div_fmas_f32 v40, v40, v56, v42
	v_div_fixup_f32 v92, v40, v92, 1.0
	v_mov_b32_e32 v105, v174
	v_mov_b32_e32 v96, v173
	v_mov_b32_e32 v104, v172
	v_mov_b32_e32 v97, v175
	v_pk_mul_f32 v[88:89], v[88:89], v[96:97]
	v_pk_mul_f32 v[102:103], v[102:103], v[104:105]
	v_pk_mul_f32 v[88:89], v[88:89], v[92:93]
	v_pk_mul_f32 v[98:99], v[102:103], v[98:99]
	v_and_b32_sdwa v44, v89, v142 dst_sel:DWORD dst_unused:UNUSED_PAD src0_sel:WORD_1 src1_sel:DWORD
	v_and_b32_sdwa v46, v88, v142 dst_sel:DWORD dst_unused:UNUSED_PAD src0_sel:WORD_1 src1_sel:DWORD
	v_and_b32_sdwa v40, v99, v142 dst_sel:DWORD dst_unused:UNUSED_PAD src0_sel:WORD_1 src1_sel:DWORD
	v_and_b32_sdwa v42, v98, v142 dst_sel:DWORD dst_unused:UNUSED_PAD src0_sel:WORD_1 src1_sel:DWORD
	v_add3_u32 v44, v89, v44, s25
	v_add3_u32 v46, v88, v46, s25
	v_add3_u32 v42, v98, v42, s25
	v_add3_u32 v40, v99, v40, s25
	v_and_b32_e32 v44, 0xffff0000, v44
	v_and_b32_e32 v46, 0xffff0000, v46
	v_or_b32_sdwa v89, v44, v40 dst_sel:DWORD dst_unused:UNUSED_PAD src0_sel:DWORD src1_sel:WORD_1
	v_or_b32_sdwa v88, v46, v42 dst_sel:DWORD dst_unused:UNUSED_PAD src0_sel:DWORD src1_sel:WORD_1
	global_store_dwordx2 v[0:1], v[88:89], off offset:48
	s_waitcnt vmcnt(6)
	v_lshlrev_b32_e32 v40, 16, v166
	v_mul_f32_e32 v40, 0xbfb8aa3b, v40
	v_exp_f32_e32 v88, v40
	v_lshlrev_b32_e32 v40, 16, v167
	v_mul_f32_e32 v40, 0xbfb8aa3b, v40
	v_exp_f32_e32 v89, v40
	v_mov_b32_e32 v96, v90
	v_mov_b32_e32 v97, v86
	v_mov_b32_e32 v86, v91
	v_pk_add_f32 v[88:89], v[88:89], 1.0 op_sel_hi:[1,0]
	v_and_b32_e32 v2, 0xffff0000, v166
	v_div_scale_f32 v40, s[0:1], v89, v89, 1.0
	v_rcp_f32_e32 v42, v40
	v_and_b32_e32 v3, 0xffff0000, v167
	v_mul_f32_e32 v2, 0xbfb8aa3b, v2
	v_mul_f32_e32 v3, 0xbfb8aa3b, v3
	v_fma_f32 v44, -v40, v42, 1.0
	v_fmac_f32_e32 v42, v44, v42
	v_div_scale_f32 v44, vcc, 1.0, v89, 1.0
	v_mul_f32_e32 v46, v44, v42
	v_fma_f32 v56, -v40, v46, v44
	v_fmac_f32_e32 v46, v56, v42
	v_fma_f32 v40, -v40, v46, v44
	v_div_scale_f32 v44, s[0:1], v88, v88, 1.0
	v_rcp_f32_e32 v56, v44
	v_div_fmas_f32 v40, v40, v42, v46
	v_div_fixup_f32 v89, v40, v89, 1.0
	v_exp_f32_e32 v2, v2
	v_fma_f32 v40, -v44, v56, 1.0
	v_fmac_f32_e32 v56, v40, v56
	v_div_scale_f32 v40, vcc, 1.0, v88, 1.0
	v_exp_f32_e32 v3, v3
	v_mul_f32_e32 v42, v40, v56
	v_fma_f32 v46, -v44, v42, v40
	v_fmac_f32_e32 v42, v46, v56
	v_fma_f32 v40, -v44, v42, v40
	v_div_fmas_f32 v40, v40, v56, v42
	v_pk_add_f32 v[2:3], v[2:3], 1.0 op_sel_hi:[1,0]
	v_div_fixup_f32 v88, v40, v88, 1.0
	v_div_scale_f32 v40, s[0:1], v3, v3, 1.0
	v_rcp_f32_e32 v42, v40
	v_pk_mul_f32 v[86:87], v[86:87], v[38:39] op_sel_hi:[1,0]
	v_pk_mul_f32 v[96:97], v[96:97], v[38:39] op_sel_hi:[1,0]
	v_fma_f32 v44, -v40, v42, 1.0
	v_fmac_f32_e32 v42, v44, v42
	v_div_scale_f32 v44, vcc, 1.0, v3, 1.0
	v_mul_f32_e32 v46, v44, v42
	v_fma_f32 v56, -v40, v46, v44
	v_fmac_f32_e32 v46, v56, v42
	v_fma_f32 v40, -v40, v46, v44
	v_div_scale_f32 v44, s[0:1], v2, v2, 1.0
	v_rcp_f32_e32 v56, v44
	v_div_fmas_f32 v40, v40, v42, v46
	v_div_fixup_f32 v3, v40, v3, 1.0
	v_fma_f32 v40, -v44, v56, 1.0
	v_fmac_f32_e32 v56, v40, v56
	v_div_scale_f32 v40, vcc, 1.0, v2, 1.0
	v_mul_f32_e32 v42, v40, v56
	v_fma_f32 v46, -v44, v42, v40
	v_fmac_f32_e32 v42, v46, v56
	v_fma_f32 v40, -v44, v42, v40
	v_div_fmas_f32 v40, v40, v56, v42
	v_div_fixup_f32 v2, v40, v2, 1.0
	v_mov_b32_e32 v99, v178
	v_mov_b32_e32 v94, v177
	v_mov_b32_e32 v98, v176
	v_mov_b32_e32 v95, v179
	v_pk_mul_f32 v[86:87], v[86:87], v[94:95]
	v_pk_mul_f32 v[96:97], v[96:97], v[98:99]
	v_pk_mul_f32 v[2:3], v[86:87], v[2:3]
	v_pk_mul_f32 v[88:89], v[96:97], v[88:89]
	v_and_b32_sdwa v44, v3, v142 dst_sel:DWORD dst_unused:UNUSED_PAD src0_sel:WORD_1 src1_sel:DWORD
	v_and_b32_sdwa v46, v2, v142 dst_sel:DWORD dst_unused:UNUSED_PAD src0_sel:WORD_1 src1_sel:DWORD
	v_and_b32_sdwa v40, v89, v142 dst_sel:DWORD dst_unused:UNUSED_PAD src0_sel:WORD_1 src1_sel:DWORD
	v_and_b32_sdwa v42, v88, v142 dst_sel:DWORD dst_unused:UNUSED_PAD src0_sel:WORD_1 src1_sel:DWORD
	v_add3_u32 v3, v3, v44, s25
	v_add3_u32 v2, v2, v46, s25
	v_add3_u32 v42, v88, v42, s25
	v_add3_u32 v40, v89, v40, s25
	v_and_b32_e32 v3, 0xffff0000, v3
	v_and_b32_e32 v2, 0xffff0000, v2
	v_or_b32_sdwa v3, v3, v40 dst_sel:DWORD dst_unused:UNUSED_PAD src0_sel:DWORD src1_sel:WORD_1
	v_or_b32_sdwa v2, v2, v42 dst_sel:DWORD dst_unused:UNUSED_PAD src0_sel:DWORD src1_sel:WORD_1
	global_store_dwordx2 v[0:1], v[2:3], off offset:64
	s_nop 0
	s_waitcnt vmcnt(6)
; __device__ __forceinline__ unsigned pk2(float lo, float hi) { return f2bf(lo) | (f2bf(hi) << 16); }
; __device__ __forceinline__ float bflo(unsigned w) { return __uint_as_float(w << 16); }
; __device__ __forceinline__ float bfhi(unsigned w) { return __uint_as_float(w & 0xffff0000u); }
; __device__ __forceinline__ float sigmoidf_(float x) { return 1.0f / (1.0f + __expf(-x)); }
; __device__ __forceinline__ void mlstm_stage_c(LAS unsigned char* lds, const bf16_t* QKO, const bf16_t* KVT, const float* G, const float* gbias, const bf16_t* DC, const float* DN, ...
;     ...
; #pragma unroll
;             for (int vb = 0; vb < 2; ++vb)
; #pragma unroll
;                 for (int gq = 0; gq < 4; ++gq) { const int v0 = wave * 64 + vb * 32 + 8 * gq + 4 * hi;
;                     const u32x2 ow = *(const u32x2*)(QKO + (size_t)(t0 + t) * 4096 + 2048 + h * 512 + v0);
;                     const f32x4 gn = *(const f32x4*)(hnorm + h * 512 + v0);
;                     const float o0 = acc[vb][tb][4 * gq] * rstd * gn.x * sigmoidf_(bflo(ow.x)), o1 = acc[vb][tb][4 * gq + 1] * rstd * gn.y * sigmoidf_(bfhi(ow.x));
;                     const float o2 = acc[vb][tb][4 * gq + 2] * rstd * gn.z * sigmoidf_(bflo(ow.y)), o3 = acc[vb][tb][4 * gq + 3] * rstd * gn.w * sigmoidf_(bfhi(ow.y));
;                     u32x2 w; w.x = pk2(o0, o1); w.y = pk2(o2, o3);
;                     *(u32x2*)(HG + (size_t)(t0 + t) * 2048 + h * 512 + v0) = w; } }
	v_lshlrev_b32_e32 v40, 16, v180
	v_mul_f32_e32 v40, 0xbfb8aa3b, v40
	v_exp_f32_e32 v82, v40
	v_and_b32_e32 v40, 0xffff0000, v180
	v_mul_f32_e32 v40, 0xbfb8aa3b, v40
	v_exp_f32_e32 v90, v40
	v_lshlrev_b32_e32 v40, 16, v181
	v_mul_f32_e32 v40, 0xbfb8aa3b, v40
	v_exp_f32_e32 v83, v40
	v_and_b32_e32 v40, 0xffff0000, v181
	v_mul_f32_e32 v40, 0xbfb8aa3b, v40
	v_exp_f32_e32 v91, v40
	v_pk_add_f32 v[82:83], v[82:83], 1.0 op_sel_hi:[1,0]
	v_mov_b32_e32 v92, v84
	v_div_scale_f32 v40, s[0:1], v83, v83, 1.0
	v_rcp_f32_e32 v42, v40
	v_mov_b32_e32 v93, v62
	v_mov_b32_e32 v62, v85
	v_pk_add_f32 v[84:85], v[90:91], 1.0 op_sel_hi:[1,0]
	v_fma_f32 v44, -v40, v42, 1.0
	v_fmac_f32_e32 v42, v44, v42
	v_div_scale_f32 v44, vcc, 1.0, v83, 1.0
	v_mul_f32_e32 v46, v44, v42
	v_fma_f32 v56, -v40, v46, v44
	v_fmac_f32_e32 v46, v56, v42
	v_fma_f32 v40, -v40, v46, v44
	v_div_scale_f32 v44, s[0:1], v82, v82, 1.0
	v_rcp_f32_e32 v56, v44
	v_div_fmas_f32 v40, v40, v42, v46
	v_div_fixup_f32 v83, v40, v83, 1.0
	v_pk_mul_f32 v[62:63], v[62:63], v[38:39] op_sel_hi:[1,0]
	v_fma_f32 v40, -v44, v56, 1.0
	v_fmac_f32_e32 v56, v40, v56
	v_div_scale_f32 v40, vcc, 1.0, v82, 1.0
	v_mul_f32_e32 v42, v40, v56
	v_fma_f32 v46, -v44, v42, v40
	v_fmac_f32_e32 v42, v46, v56
	v_fma_f32 v40, -v44, v42, v40
	v_div_fmas_f32 v40, v40, v56, v42
	v_div_fixup_f32 v82, v40, v82, 1.0
	v_div_scale_f32 v40, s[0:1], v85, v85, 1.0
	v_rcp_f32_e32 v42, v40
	v_pk_mul_f32 v[92:93], v[92:93], v[38:39] op_sel_hi:[1,0]
	v_fma_f32 v44, -v40, v42, 1.0
	v_fmac_f32_e32 v42, v44, v42
	v_div_scale_f32 v44, vcc, 1.0, v85, 1.0
	v_mul_f32_e32 v46, v44, v42
	v_fma_f32 v56, -v40, v46, v44
	v_fmac_f32_e32 v46, v56, v42
	v_fma_f32 v40, -v40, v46, v44
	v_div_scale_f32 v44, s[0:1], v84, v84, 1.0
	v_rcp_f32_e32 v56, v44
	v_div_fmas_f32 v40, v40, v42, v46
	v_div_fixup_f32 v85, v40, v85, 1.0
	v_fma_f32 v40, -v44, v56, 1.0
	v_fmac_f32_e32 v56, v40, v56
	v_div_scale_f32 v40, vcc, 1.0, v84, 1.0
	v_mul_f32_e32 v42, v40, v56
	v_fma_f32 v46, -v44, v42, v40
	v_fmac_f32_e32 v42, v46, v56
	v_fma_f32 v40, -v44, v42, v40
	v_div_fmas_f32 v40, v40, v56, v42
	v_div_fixup_f32 v84, v40, v84, 1.0
	v_mov_b32_e32 v95, v186
	v_mov_b32_e32 v88, v185
	v_mov_b32_e32 v94, v184
	v_mov_b32_e32 v89, v187
	v_pk_mul_f32 v[62:63], v[62:63], v[88:89]
	v_pk_mul_f32 v[92:93], v[92:93], v[94:95]
	v_pk_mul_f32 v[62:63], v[62:63], v[84:85]
	v_pk_mul_f32 v[82:83], v[92:93], v[82:83]
	v_and_b32_sdwa v44, v63, v142 dst_sel:DWORD dst_unused:UNUSED_PAD src0_sel:WORD_1 src1_sel:DWORD
	v_and_b32_sdwa v46, v62, v142 dst_sel:DWORD dst_unused:UNUSED_PAD src0_sel:WORD_1 src1_sel:DWORD
	v_and_b32_sdwa v40, v83, v142 dst_sel:DWORD dst_unused:UNUSED_PAD src0_sel:WORD_1 src1_sel:DWORD
	v_and_b32_sdwa v42, v82, v142 dst_sel:DWORD dst_unused:UNUSED_PAD src0_sel:WORD_1 src1_sel:DWORD
	v_add3_u32 v44, v63, v44, s25
	v_add3_u32 v46, v62, v46, s25
	v_add3_u32 v42, v82, v42, s25
	v_add3_u32 v40, v83, v40, s25
	v_and_b32_e32 v44, 0xffff0000, v44
	v_and_b32_e32 v46, 0xffff0000, v46
	v_or_b32_sdwa v63, v44, v40 dst_sel:DWORD dst_unused:UNUSED_PAD src0_sel:DWORD src1_sel:WORD_1
	v_or_b32_sdwa v62, v46, v42 dst_sel:DWORD dst_unused:UNUSED_PAD src0_sel:DWORD src1_sel:WORD_1
	global_store_dwordx2 v[0:1], v[62:63], off offset:80
	s_waitcnt vmcnt(6)
	v_lshlrev_b32_e32 v40, 16, v182
	v_mul_f32_e32 v40, 0xbfb8aa3b, v40
	v_exp_f32_e32 v62, v40
	v_lshlrev_b32_e32 v40, 16, v183
	v_mul_f32_e32 v40, 0xbfb8aa3b, v40
	v_exp_f32_e32 v63, v40
	v_mov_b32_e32 v87, v52
	v_and_b32_e32 v2, 0xffff0000, v182
	v_and_b32_e32 v3, 0xffff0000, v183
	v_pk_add_f32 v[62:63], v[62:63], 1.0 op_sel_hi:[1,0]
	v_mul_f32_e32 v2, 0xbfb8aa3b, v2
	v_div_scale_f32 v40, s[0:1], v63, v63, 1.0
	v_rcp_f32_e32 v42, v40
	v_mul_f32_e32 v3, 0xbfb8aa3b, v3
	v_exp_f32_e32 v2, v2
	v_exp_f32_e32 v3, v3
	v_fma_f32 v44, -v40, v42, 1.0
	v_fmac_f32_e32 v42, v44, v42
	v_div_scale_f32 v44, vcc, 1.0, v63, 1.0
	v_mul_f32_e32 v46, v44, v42
	v_fma_f32 v52, -v40, v46, v44
	v_fmac_f32_e32 v46, v52, v42
	v_fma_f32 v40, -v40, v46, v44
	v_div_scale_f32 v44, s[0:1], v62, v62, 1.0
	v_rcp_f32_e32 v52, v44
	v_div_fmas_f32 v40, v40, v42, v46
	v_div_fixup_f32 v63, v40, v63, 1.0
	v_pk_add_f32 v[2:3], v[2:3], 1.0 op_sel_hi:[1,0]
	v_fma_f32 v40, -v44, v52, 1.0
	v_fmac_f32_e32 v52, v40, v52
	v_div_scale_f32 v40, vcc, 1.0, v62, 1.0
	v_mul_f32_e32 v42, v40, v52
	v_fma_f32 v46, -v44, v42, v40
	v_fmac_f32_e32 v42, v46, v52
	v_fma_f32 v40, -v44, v42, v40
	v_div_fmas_f32 v40, v40, v52, v42
	v_div_fixup_f32 v62, v40, v62, 1.0
	v_div_scale_f32 v40, s[0:1], v3, v3, 1.0
	v_rcp_f32_e32 v42, v40
	v_mov_b32_e32 v86, v54
	v_mov_b32_e32 v52, v55
	v_pk_mul_f32 v[52:53], v[52:53], v[38:39] op_sel_hi:[1,0]
	v_fma_f32 v44, -v40, v42, 1.0
	v_fmac_f32_e32 v42, v44, v42
	v_div_scale_f32 v44, vcc, 1.0, v3, 1.0
	v_mul_f32_e32 v46, v44, v42
	v_fma_f32 v54, -v40, v46, v44
	v_fmac_f32_e32 v46, v54, v42
	v_fma_f32 v40, -v40, v46, v44
	v_div_scale_f32 v44, s[0:1], v2, v2, 1.0
	v_rcp_f32_e32 v54, v44
	v_div_fmas_f32 v40, v40, v42, v46
	v_div_fixup_f32 v3, v40, v3, 1.0
	v_pk_mul_f32 v[86:87], v[86:87], v[38:39] op_sel_hi:[1,0]
	v_fma_f32 v40, -v44, v54, 1.0
	v_fmac_f32_e32 v54, v40, v54
	v_div_scale_f32 v40, vcc, 1.0, v2, 1.0
	v_mul_f32_e32 v42, v40, v54
	v_fma_f32 v46, -v44, v42, v40
	v_fmac_f32_e32 v42, v46, v54
	v_fma_f32 v40, -v44, v42, v40
	v_div_fmas_f32 v40, v40, v54, v42
	v_div_fixup_f32 v2, v40, v2, 1.0
	v_mov_b32_e32 v89, v190
	v_mov_b32_e32 v84, v189
	v_mov_b32_e32 v88, v188
	v_mov_b32_e32 v85, v191
	v_pk_mul_f32 v[52:53], v[52:53], v[84:85]
	v_pk_mul_f32 v[86:87], v[86:87], v[88:89]
	v_pk_mul_f32 v[2:3], v[52:53], v[2:3]
	v_pk_mul_f32 v[62:63], v[86:87], v[62:63]
; __device__ __forceinline__ unsigned pk2(float lo, float hi) { return f2bf(lo) | (f2bf(hi) << 16); }
; __device__ __forceinline__ float bflo(unsigned w) { return __uint_as_float(w << 16); }
; __device__ __forceinline__ float bfhi(unsigned w) { return __uint_as_float(w & 0xffff0000u); }
; __device__ __forceinline__ float sigmoidf_(float x) { return 1.0f / (1.0f + __expf(-x)); }
; __device__ __forceinline__ void mlstm_stage_c(LAS unsigned char* lds, const bf16_t* QKO, const bf16_t* KVT, const float* G, const float* gbias, const bf16_t* DC, const float* DN, ...
;     ...
;         for (int tb = 0; tb < 2; ++tb) { const int t = tb * 32 + r32; float tot = 0.f;
; #pragma unroll
;             for (int w = 0; w < 8; ++w) tot += sSsq[w * 64 + t];
;             const float rstd = 1.0f / sqrtf(tot * (1.0f / 512.0f) + EPS);
; #pragma unroll
;             for (int vb = 0; vb < 2; ++vb)
; #pragma unroll
;                 for (int gq = 0; gq < 4; ++gq) { const int v0 = wave * 64 + vb * 32 + 8 * gq + 4 * hi;
;                     const u32x2 ow = *(const u32x2*)(QKO + (size_t)(t0 + t) * 4096 + 2048 + h * 512 + v0);
;                     const f32x4 gn = *(const f32x4*)(hnorm + h * 512 + v0);
;                     const float o0 = acc[vb][tb][4 * gq] * rstd * gn.x * sigmoidf_(bflo(ow.x)), o1 = acc[vb][tb][4 * gq + 1] * rstd * gn.y * sigmoidf_(bfhi(ow.x));
;                     const float o2 = acc[vb][tb][4 * gq + 2] * rstd * gn.z * sigmoidf_(bflo(ow.y)), o3 = acc[vb][tb][4 * gq + 3] * rstd * gn.w * sigmoidf_(bfhi(ow.y));
;                     u32x2 w; w.x = pk2(o0, o1); w.y = pk2(o2, o3);
;                     *(u32x2*)(HG + (size_t)(t0 + t) * 2048 + h * 512 + v0) = w; } }
	v_and_b32_sdwa v44, v3, v142 dst_sel:DWORD dst_unused:UNUSED_PAD src0_sel:WORD_1 src1_sel:DWORD
	v_and_b32_sdwa v46, v2, v142 dst_sel:DWORD dst_unused:UNUSED_PAD src0_sel:WORD_1 src1_sel:DWORD
	v_and_b32_sdwa v40, v63, v142 dst_sel:DWORD dst_unused:UNUSED_PAD src0_sel:WORD_1 src1_sel:DWORD
	v_and_b32_sdwa v42, v62, v142 dst_sel:DWORD dst_unused:UNUSED_PAD src0_sel:WORD_1 src1_sel:DWORD
	v_add3_u32 v3, v3, v44, s25
	v_add3_u32 v2, v2, v46, s25
	v_add3_u32 v42, v62, v42, s25
	v_add3_u32 v40, v63, v40, s25
	v_and_b32_e32 v3, 0xffff0000, v3
	v_and_b32_e32 v2, 0xffff0000, v2
	v_or_b32_sdwa v3, v3, v40 dst_sel:DWORD dst_unused:UNUSED_PAD src0_sel:DWORD src1_sel:WORD_1
	v_or_b32_sdwa v2, v2, v42 dst_sel:DWORD dst_unused:UNUSED_PAD src0_sel:DWORD src1_sel:WORD_1
	global_store_dwordx2 v[0:1], v[2:3], off offset:96
	v_and_b32_e32 v3, 0xffff0000, v206
	v_mul_f32_e32 v3, 0xbfb8aa3b, v3
	v_lshlrev_b32_e32 v2, 16, v206
	v_exp_f32_e32 v62, v3
	v_lshlrev_b32_e32 v3, 16, v207
	v_mul_f32_e32 v2, 0xbfb8aa3b, v2
	v_mul_f32_e32 v3, 0xbfb8aa3b, v3
	v_exp_f32_e32 v2, v2
	v_exp_f32_e32 v3, v3
	v_and_b32_e32 v40, 0xffff0000, v207
	v_mul_f32_e32 v40, 0xbfb8aa3b, v40
	v_exp_f32_e32 v63, v40
	v_pk_add_f32 v[2:3], v[2:3], 1.0 op_sel_hi:[1,0]
	v_mov_b32_e32 v81, v48
	v_div_scale_f32 v40, s[0:1], v3, v3, 1.0
	v_rcp_f32_e32 v42, v40
	v_mov_b32_e32 v80, v50
	v_pk_mul_f32 v[80:81], v[80:81], v[38:39] op_sel_hi:[1,0]
	v_fma_f32 v44, -v40, v42, 1.0
	v_fmac_f32_e32 v42, v44, v42
	v_div_scale_f32 v44, vcc, 1.0, v3, 1.0
	v_mul_f32_e32 v46, v44, v42
	v_fma_f32 v48, -v40, v46, v44
	v_fmac_f32_e32 v46, v48, v42
	v_fma_f32 v40, -v40, v46, v44
	v_div_scale_f32 v44, s[0:1], v2, v2, 1.0
	v_rcp_f32_e32 v48, v44
	v_div_fmas_f32 v40, v40, v42, v46
	v_div_fixup_f32 v3, v40, v3, 1.0
	v_fma_f32 v40, -v44, v48, 1.0
	v_fmac_f32_e32 v48, v40, v48
	v_div_scale_f32 v40, vcc, 1.0, v2, 1.0
	v_mul_f32_e32 v42, v40, v48
	v_fma_f32 v46, -v44, v42, v40
	v_fmac_f32_e32 v42, v46, v48
	v_fma_f32 v40, -v44, v42, v40
	v_div_fmas_f32 v40, v40, v48, v42
	v_mov_b32_e32 v48, v51
	v_pk_add_f32 v[50:51], v[62:63], 1.0 op_sel_hi:[1,0]
	v_div_fixup_f32 v2, v40, v2, 1.0
	v_div_scale_f32 v40, s[0:1], v51, v51, 1.0
	v_rcp_f32_e32 v42, v40
	v_pk_mul_f32 v[48:49], v[48:49], v[38:39] op_sel_hi:[1,0]
	v_fma_f32 v38, -v40, v42, 1.0
	v_fmac_f32_e32 v42, v38, v42
	v_div_scale_f32 v38, vcc, 1.0, v51, 1.0
	v_mul_f32_e32 v44, v38, v42
	v_fma_f32 v46, -v40, v44, v38
	v_fmac_f32_e32 v44, v46, v42
	v_fma_f32 v38, -v40, v44, v38
	v_div_scale_f32 v40, s[0:1], v50, v50, 1.0
	v_readlane_b32 s0, v249, 58
	v_readlane_b32 s1, v249, 59
	v_rcp_f32_e32 v46, v40
	v_div_fmas_f32 v38, v38, v42, v44
	v_div_fixup_f32 v51, v38, v51, 1.0
	v_fma_f32 v38, -v40, v46, 1.0
	v_fmac_f32_e32 v46, v38, v46
	v_div_scale_f32 v38, vcc, 1.0, v50, 1.0
	v_mul_f32_e32 v42, v38, v46
	v_fma_f32 v44, -v40, v42, v38
	v_fmac_f32_e32 v42, v44, v46
	v_fma_f32 v38, -v40, v42, v38
	v_div_fmas_f32 v38, v38, v46, v42
	v_div_fixup_f32 v50, v38, v50, 1.0
	v_mov_b32_e32 v83, v194
	v_mov_b32_e32 v54, v193
	v_mov_b32_e32 v82, v192
	v_mov_b32_e32 v55, v195
	v_pk_mul_f32 v[52:53], v[48:49], v[54:55]
	v_or_b32_e32 v54, s18, v71
	v_ashrrev_i32_e32 v55, 31, v54
	v_lshlrev_b64 v[48:49], 13, v[54:55]
	v_lshl_add_u64 v[48:49], s[0:1], 0, v[48:49]
	v_lshl_add_u64 v[48:49], v[48:49], 0, s[78:79]
	v_lshl_add_u64 v[62:63], v[48:49], 0, v[78:79]
	v_add_co_u32_e64 v48, s[0:1], s27, v62
	v_pk_mul_f32 v[80:81], v[80:81], v[82:83]
	s_nop 0
	v_addc_co_u32_e64 v49, s[0:1], 0, v63, s[0:1]
	global_load_dwordx2 v[196:197], v[48:49], off
	v_pk_mul_f32 v[2:3], v[80:81], v[2:3]
	v_pk_mul_f32 v[50:51], v[52:53], v[50:51]
	v_and_b32_sdwa v38, v3, v142 dst_sel:DWORD dst_unused:UNUSED_PAD src0_sel:WORD_1 src1_sel:DWORD
	v_and_b32_sdwa v40, v2, v142 dst_sel:DWORD dst_unused:UNUSED_PAD src0_sel:WORD_1 src1_sel:DWORD
	v_add3_u32 v2, v2, v40, s25
	v_add3_u32 v3, v3, v38, s25
	v_and_b32_sdwa v38, v51, v142 dst_sel:DWORD dst_unused:UNUSED_PAD src0_sel:WORD_1 src1_sel:DWORD
	v_and_b32_sdwa v40, v50, v142 dst_sel:DWORD dst_unused:UNUSED_PAD src0_sel:WORD_1 src1_sel:DWORD
	v_add3_u32 v38, v51, v38, s25
	v_add3_u32 v40, v50, v40, s25
	v_and_b32_e32 v38, 0xffff0000, v38
	v_and_b32_e32 v40, 0xffff0000, v40
	v_or_b32_sdwa v3, v38, v3 dst_sel:DWORD dst_unused:UNUSED_PAD src0_sel:DWORD src1_sel:WORD_1
	v_or_b32_sdwa v2, v40, v2 dst_sel:DWORD dst_unused:UNUSED_PAD src0_sel:DWORD src1_sel:WORD_1
	global_store_dwordx2 v[0:1], v[2:3], off offset:112
	v_add_f32_e32 v38, 0, v39
	v_add_f32_e32 v38, v38, v41
	v_add_f32_e32 v38, v38, v43
	v_add_f32_e32 v38, v38, v45
	v_add_f32_e32 v38, v38, v47
	v_add_f32_e32 v38, v38, v57
	v_add_f32_e32 v38, v38, v59
	v_add_f32_e32 v38, v38, v61
	v_fmamk_f32 v38, v38, 0x3b000000, v138
	v_mul_f32_e32 v39, 0x4f800000, v38
	v_cmp_gt_f32_e32 vcc, s26, v38
	v_mov_b32_e32 v50, v32
	v_mov_b32_e32 v51, v34
	v_cndmask_b32_e32 v38, v38, v39, vcc
	v_sqrt_f32_e32 v39, v38
	v_mov_b32_e32 v52, v152
	v_add_u32_e32 v40, -1, v39
	v_fma_f32 v41, -v40, v39, v38
	v_cmp_ge_f32_e64 s[0:1], 0, v41
	v_add_u32_e32 v41, 1, v39
	v_mov_b32_e32 v53, v154
	v_cndmask_b32_e64 v40, v39, v40, s[0:1]
	v_fma_f32 v39, -v41, v39, v38
	v_cmp_lt_f32_e64 s[0:1], 0, v39
	s_nop 1
	v_cndmask_b32_e64 v39, v40, v41, s[0:1]
	v_mul_f32_e32 v40, 0x37800000, v39
	v_cndmask_b32_e32 v39, v39, v40, vcc
	v_cmp_class_f32_e32 vcc, v38, v139
	s_nop 1
	v_cndmask_b32_e32 v38, v39, v38, vcc
	v_div_scale_f32 v39, s[0:1], v38, v38, 1.0
	v_rcp_f32_e32 v40, v39
	s_nop 0
	v_fma_f32 v41, -v39, v40, 1.0
	v_fmac_f32_e32 v40, v41, v40
	v_div_scale_f32 v41, vcc, 1.0, v38, 1.0
	v_mul_f32_e32 v42, v41, v40
	v_fma_f32 v43, -v39, v42, v41
	v_fmac_f32_e32 v42, v43, v40
	v_fma_f32 v39, -v39, v42, v41
	v_div_fmas_f32 v39, v39, v40, v42
	v_lshlrev_b64 v[40:41], 12, v[54:55]
	v_lshl_add_u64 v[42:43], v[62:63], 0, s[56:57]
	global_load_dwordx2 v[198:199], v[42:43], off offset:112
	global_load_dwordx2 v[200:201], v[42:43], off offset:16
	global_load_dwordx2 v[202:203], v[42:43], off offset:32
	global_load_dwordx2 v[208:209], v[42:43], off offset:48
	global_load_dwordx2 v[210:211], v[42:43], off offset:64
	global_load_dwordx2 v[212:213], v[42:43], off offset:80
	global_load_dwordx2 v[214:215], v[42:43], off offset:96
	v_div_fixup_f32 v38, v39, v38, 1.0
	v_lshl_add_u64 v[44:45], s[4:5], 0, v[40:41]
	s_waitcnt vmcnt(8)
; __device__ __forceinline__ unsigned pk2(float lo, float hi) { return f2bf(lo) | (f2bf(hi) << 16); }
; __device__ __forceinline__ float bflo(unsigned w) { return __uint_as_float(w << 16); }
; __device__ __forceinline__ float bfhi(unsigned w) { return __uint_as_float(w & 0xffff0000u); }
; __device__ __forceinline__ float sigmoidf_(float x) { return 1.0f / (1.0f + __expf(-x)); }
; __device__ __forceinline__ void mlstm_stage_c(LAS unsigned char* lds, const bf16_t* QKO, const bf16_t* KVT, const float* G, const float* gbias, const bf16_t* DC, const float* DN, ...
;     ...
;         for (int tb = 0; tb < 2; ++tb) { const int t = tb * 32 + r32; float tot = 0.f;
; #pragma unroll
;             for (int w = 0; w < 8; ++w) tot += sSsq[w * 64 + t];
;             const float rstd = 1.0f / sqrtf(tot * (1.0f / 512.0f) + EPS);
; #pragma unroll
;             for (int vb = 0; vb < 2; ++vb)
; #pragma unroll
;                 for (int gq = 0; gq < 4; ++gq) { const int v0 = wave * 64 + vb * 32 + 8 * gq + 4 * hi;
;                     const u32x2 ow = *(const u32x2*)(QKO + (size_t)(t0 + t) * 4096 + 2048 + h * 512 + v0);
;                     const f32x4 gn = *(const f32x4*)(hnorm + h * 512 + v0);
;                     const float o0 = acc[vb][tb][4 * gq] * rstd * gn.x * sigmoidf_(bflo(ow.x)), o1 = acc[vb][tb][4 * gq + 1] * rstd * gn.y * sigmoidf_(bfhi(ow.x));
;                     const float o2 = acc[vb][tb][4 * gq + 2] * rstd * gn.z * sigmoidf_(bflo(ow.y)), o3 = acc[vb][tb][4 * gq + 3] * rstd * gn.w * sigmoidf_(bfhi(ow.y));
;                     u32x2 w; w.x = pk2(o0, o1); w.y = pk2(o2, o3);
;                     *(u32x2*)(HG + (size_t)(t0 + t) * 2048 + h * 512 + v0) = w; } }
	v_lshlrev_b32_e32 v39, 16, v196
	v_mul_f32_e32 v39, 0xbfb8aa3b, v39
	v_exp_f32_e32 v46, v39
	v_and_b32_e32 v39, 0xffff0000, v196
	v_mul_f32_e32 v39, 0xbfb8aa3b, v39
	v_exp_f32_e32 v48, v39
	v_lshlrev_b32_e32 v39, 16, v197
	v_mul_f32_e32 v39, 0xbfb8aa3b, v39
	v_exp_f32_e32 v47, v39
	v_and_b32_e32 v39, 0xffff0000, v197
	v_mul_f32_e32 v39, 0xbfb8aa3b, v39
	v_exp_f32_e32 v49, v39
	v_pk_add_f32 v[46:47], v[46:47], 1.0 op_sel_hi:[1,0]
	v_pk_mul_f32 v[50:51], v[50:51], v[38:39] op_sel_hi:[1,0]
	v_div_scale_f32 v32, s[0:1], v47, v47, 1.0
	v_rcp_f32_e32 v34, v32
	v_pk_mul_f32 v[50:51], v[52:53], v[50:51]
	v_mov_b32_e32 v53, v30
	v_mov_b32_e32 v52, v36
	v_fma_f32 v0, -v32, v34, 1.0
	v_fmac_f32_e32 v34, v0, v34
	v_div_scale_f32 v0, vcc, 1.0, v47, 1.0
	v_mul_f32_e32 v2, v0, v34
	v_fma_f32 v39, -v32, v2, v0
	v_fmac_f32_e32 v2, v39, v34
	v_fma_f32 v0, -v32, v2, v0
	v_div_scale_f32 v32, s[0:1], v46, v46, 1.0
	v_rcp_f32_e32 v39, v32
	v_div_fmas_f32 v0, v0, v34, v2
	v_div_fixup_f32 v47, v0, v47, 1.0
	v_fma_f32 v0, -v32, v39, 1.0
	v_fmac_f32_e32 v39, v0, v39
	v_div_scale_f32 v0, vcc, 1.0, v46, 1.0
	v_mul_f32_e32 v2, v0, v39
	v_fma_f32 v34, -v32, v2, v0
	v_fmac_f32_e32 v2, v34, v39
	v_fma_f32 v0, -v32, v2, v0
	v_mov_b32_e32 v34, v33
	v_pk_add_f32 v[32:33], v[48:49], 1.0 op_sel_hi:[1,0]
	v_div_fmas_f32 v0, v0, v39, v2
	v_div_scale_f32 v39, s[0:1], v33, v33, 1.0
	v_rcp_f32_e32 v48, v39
	v_pk_mul_f32 v[34:35], v[34:35], v[38:39] op_sel_hi:[1,0]
	v_mov_b32_e32 v2, v153
	v_div_fixup_f32 v46, v0, v46, 1.0
	v_mov_b32_e32 v3, v155
	v_pk_mul_f32 v[0:1], v[2:3], v[34:35]
	v_fma_f32 v2, -v39, v48, 1.0
	v_fmac_f32_e32 v48, v2, v48
	v_div_scale_f32 v2, vcc, 1.0, v33, 1.0
	v_mul_f32_e32 v3, v2, v48
	v_fma_f32 v34, -v39, v3, v2
	v_fmac_f32_e32 v3, v34, v48
	v_fma_f32 v2, -v39, v3, v2
	v_div_scale_f32 v34, s[0:1], v32, v32, 1.0
	v_div_fmas_f32 v2, v2, v48, v3
	v_rcp_f32_e32 v35, v34
	v_div_fixup_f32 v3, v2, v33, 1.0
	v_pk_mul_f32 v[46:47], v[50:51], v[46:47]
	v_fma_f32 v2, -v34, v35, 1.0
	v_fmac_f32_e32 v35, v2, v35
	v_div_scale_f32 v2, vcc, 1.0, v32, 1.0
	v_mul_f32_e32 v33, v2, v35
	v_fma_f32 v39, -v34, v33, v2
	v_fmac_f32_e32 v33, v39, v35
	v_fma_f32 v2, -v34, v33, v2
	v_div_fmas_f32 v2, v2, v35, v33
	v_div_fixup_f32 v2, v2, v32, 1.0
	v_pk_mul_f32 v[0:1], v[0:1], v[2:3]
	v_and_b32_sdwa v3, v46, v142 dst_sel:DWORD dst_unused:UNUSED_PAD src0_sel:WORD_1 src1_sel:DWORD
	v_add3_u32 v32, v46, v3, s25
	v_and_b32_sdwa v3, v1, v142 dst_sel:DWORD dst_unused:UNUSED_PAD src0_sel:WORD_1 src1_sel:DWORD
	v_and_b32_sdwa v33, v0, v142 dst_sel:DWORD dst_unused:UNUSED_PAD src0_sel:WORD_1 src1_sel:DWORD
	v_and_b32_sdwa v2, v47, v142 dst_sel:DWORD dst_unused:UNUSED_PAD src0_sel:WORD_1 src1_sel:DWORD
	v_add3_u32 v1, v1, v3, s25
	v_add3_u32 v0, v0, v33, s25
	v_add3_u32 v2, v47, v2, s25
	v_and_b32_e32 v1, 0xffff0000, v1
	v_and_b32_e32 v0, 0xffff0000, v0
	v_or_b32_sdwa v3, v1, v2 dst_sel:DWORD dst_unused:UNUSED_PAD src0_sel:DWORD src1_sel:WORD_1
	v_or_b32_sdwa v2, v0, v32 dst_sel:DWORD dst_unused:UNUSED_PAD src0_sel:DWORD src1_sel:WORD_1
	v_lshl_add_u64 v[0:1], v[44:45], 0, v[78:79]
	global_store_dwordx2 v[0:1], v[2:3], off
	s_nop 0
	s_waitcnt vmcnt(6)
	v_lshlrev_b32_e32 v39, 16, v200
	v_mul_f32_e32 v39, 0xbfb8aa3b, v39
	v_exp_f32_e32 v50, v39
	v_and_b32_e32 v39, 0xffff0000, v200
	v_mul_f32_e32 v39, 0xbfb8aa3b, v39
	v_exp_f32_e32 v48, v39
	v_lshlrev_b32_e32 v39, 16, v201
	v_mul_f32_e32 v39, 0xbfb8aa3b, v39
	v_exp_f32_e32 v51, v39
	v_and_b32_e32 v39, 0xffff0000, v201
	v_mul_f32_e32 v39, 0xbfb8aa3b, v39
	v_exp_f32_e32 v49, v39
	v_pk_add_f32 v[50:51], v[50:51], 1.0 op_sel_hi:[1,0]
	v_pk_mul_f32 v[52:53], v[52:53], v[38:39] op_sel_hi:[1,0]
	v_div_scale_f32 v30, s[0:1], v51, v51, 1.0
	v_rcp_f32_e32 v36, v30
	v_mov_b32_e32 v54, v160
	v_fma_f32 v32, -v30, v36, 1.0
	v_fmac_f32_e32 v36, v32, v36
	v_div_scale_f32 v32, vcc, 1.0, v51, 1.0
	v_mov_b32_e32 v55, v162
	v_mul_f32_e32 v34, v32, v36
	v_fma_f32 v39, -v30, v34, v32
	v_fmac_f32_e32 v34, v39, v36
	v_fma_f32 v30, -v30, v34, v32
	v_div_scale_f32 v32, s[0:1], v50, v50, 1.0
	v_rcp_f32_e32 v39, v32
	v_div_fmas_f32 v30, v30, v36, v34
	v_div_fixup_f32 v51, v30, v51, 1.0
	v_pk_mul_f32 v[52:53], v[54:55], v[52:53]
	v_fma_f32 v30, -v32, v39, 1.0
	v_fmac_f32_e32 v39, v30, v39
	v_div_scale_f32 v30, vcc, 1.0, v50, 1.0
	v_mul_f32_e32 v34, v30, v39
	v_fma_f32 v36, -v32, v34, v30
	v_fmac_f32_e32 v34, v36, v39
	v_fma_f32 v30, -v32, v34, v30
	v_div_fmas_f32 v30, v30, v39, v34
	v_div_fixup_f32 v50, v30, v50, 1.0
	v_mov_b32_e32 v30, v37
	v_pk_add_f32 v[36:37], v[48:49], 1.0 op_sel_hi:[1,0]
	v_mov_b32_e32 v34, v161
	v_div_scale_f32 v32, s[0:1], v37, v37, 1.0
	v_rcp_f32_e32 v39, v32
	v_pk_mul_f32 v[50:51], v[52:53], v[50:51]
	v_fma_f32 v33, -v32, v39, 1.0
	v_pk_mul_f32 v[30:31], v[30:31], v[38:39] op_sel_hi:[1,0]
	v_fmac_f32_e32 v39, v33, v39
	v_div_scale_f32 v33, vcc, 1.0, v37, 1.0
	v_mov_b32_e32 v35, v163
	v_pk_mul_f32 v[30:31], v[34:35], v[30:31]
	v_mul_f32_e32 v34, v33, v39
	v_fma_f32 v35, -v32, v34, v33
	v_fmac_f32_e32 v34, v35, v39
	v_div_scale_f32 v35, s[0:1], v36, v36, 1.0
	v_rcp_f32_e32 v48, v35
	v_fma_f32 v32, -v32, v34, v33
	v_div_fmas_f32 v32, v32, v39, v34
	v_div_fixup_f32 v33, v32, v37, 1.0
	v_fma_f32 v32, -v35, v48, 1.0
	v_fmac_f32_e32 v48, v32, v48
	v_div_scale_f32 v32, vcc, 1.0, v36, 1.0
	v_mul_f32_e32 v34, v32, v48
	v_fma_f32 v37, -v35, v34, v32
	v_fmac_f32_e32 v34, v37, v48
	v_fma_f32 v32, -v35, v34, v32
	v_div_fmas_f32 v32, v32, v48, v34
	v_div_fixup_f32 v32, v32, v36, 1.0
	v_pk_mul_f32 v[30:31], v[30:31], v[32:33]
	v_and_b32_sdwa v32, v51, v142 dst_sel:DWORD dst_unused:UNUSED_PAD src0_sel:WORD_1 src1_sel:DWORD
	v_and_b32_sdwa v34, v31, v142 dst_sel:DWORD dst_unused:UNUSED_PAD src0_sel:WORD_1 src1_sel:DWORD
	v_and_b32_sdwa v35, v30, v142 dst_sel:DWORD dst_unused:UNUSED_PAD src0_sel:WORD_1 src1_sel:DWORD
	v_and_b32_sdwa v33, v50, v142 dst_sel:DWORD dst_unused:UNUSED_PAD src0_sel:WORD_1 src1_sel:DWORD
	v_add3_u32 v31, v31, v34, s25
	v_add3_u32 v30, v30, v35, s25
	v_add3_u32 v33, v50, v33, s25
	v_add3_u32 v32, v51, v32, s25
	v_and_b32_e32 v31, 0xffff0000, v31
	v_and_b32_e32 v30, 0xffff0000, v30
	v_or_b32_sdwa v31, v31, v32 dst_sel:DWORD dst_unused:UNUSED_PAD src0_sel:DWORD src1_sel:WORD_1
	v_or_b32_sdwa v30, v30, v33 dst_sel:DWORD dst_unused:UNUSED_PAD src0_sel:DWORD src1_sel:WORD_1
	global_store_dwordx2 v[0:1], v[30:31], off offset:16
	s_waitcnt vmcnt(6)
; __device__ __forceinline__ unsigned pk2(float lo, float hi) { return f2bf(lo) | (f2bf(hi) << 16); }
; __device__ __forceinline__ float bflo(unsigned w) { return __uint_as_float(w << 16); }
; __device__ __forceinline__ float bfhi(unsigned w) { return __uint_as_float(w & 0xffff0000u); }
; __device__ __forceinline__ float sigmoidf_(float x) { return 1.0f / (1.0f + __expf(-x)); }
; __device__ __forceinline__ void mlstm_stage_c(LAS unsigned char* lds, const bf16_t* QKO, const bf16_t* KVT, const float* G, const float* gbias, const bf16_t* DC, const float* DN, ...
;     ...
;         for (int tb = 0; tb < 2; ++tb) { const int t = tb * 32 + r32; float tot = 0.f;
; #pragma unroll
;             for (int w = 0; w < 8; ++w) tot += sSsq[w * 64 + t];
;             const float rstd = 1.0f / sqrtf(tot * (1.0f / 512.0f) + EPS);
; #pragma unroll
;             for (int vb = 0; vb < 2; ++vb)
; #pragma unroll
;                 for (int gq = 0; gq < 4; ++gq) { const int v0 = wave * 64 + vb * 32 + 8 * gq + 4 * hi;
;                     const u32x2 ow = *(const u32x2*)(QKO + (size_t)(t0 + t) * 4096 + 2048 + h * 512 + v0);
;                     const f32x4 gn = *(const f32x4*)(hnorm + h * 512 + v0);
;                     const float o0 = acc[vb][tb][4 * gq] * rstd * gn.x * sigmoidf_(bflo(ow.x)), o1 = acc[vb][tb][4 * gq + 1] * rstd * gn.y * sigmoidf_(bfhi(ow.x));
;                     const float o2 = acc[vb][tb][4 * gq + 2] * rstd * gn.z * sigmoidf_(bflo(ow.y)), o3 = acc[vb][tb][4 * gq + 3] * rstd * gn.w * sigmoidf_(bfhi(ow.y));
;                     u32x2 w; w.x = pk2(o0, o1); w.y = pk2(o2, o3);
;                     *(u32x2*)(HG + (size_t)(t0 + t) * 2048 + h * 512 + v0) = w; } }
	v_and_b32_e32 v35, 0xffff0000, v202
	v_mul_f32_e32 v35, 0xbfb8aa3b, v35
	v_lshlrev_b32_e32 v34, 16, v202
	v_exp_f32_e32 v36, v35
	v_lshlrev_b32_e32 v35, 16, v203
	v_mul_f32_e32 v34, 0xbfb8aa3b, v34
	v_mul_f32_e32 v35, 0xbfb8aa3b, v35
	v_exp_f32_e32 v34, v34
	v_exp_f32_e32 v35, v35
	v_and_b32_e32 v37, 0xffff0000, v203
	v_mov_b32_e32 v45, v26
	v_mov_b32_e32 v44, v28
	v_pk_add_f32 v[34:35], v[34:35], 1.0 op_sel_hi:[1,0]
	v_pk_mul_f32 v[44:45], v[44:45], v[38:39] op_sel_hi:[1,0]
	v_div_scale_f32 v26, s[0:1], v35, v35, 1.0
	v_rcp_f32_e32 v28, v26
	v_mul_f32_e32 v37, 0xbfb8aa3b, v37
	v_exp_f32_e32 v37, v37
	v_mov_b32_e32 v48, v168
	v_fma_f32 v30, -v26, v28, 1.0
	v_fmac_f32_e32 v28, v30, v28
	v_div_scale_f32 v30, vcc, 1.0, v35, 1.0
	v_mov_b32_e32 v49, v170
	v_mul_f32_e32 v32, v30, v28
	v_fma_f32 v39, -v26, v32, v30
	v_fmac_f32_e32 v32, v39, v28
	v_fma_f32 v26, -v26, v32, v30
	v_div_scale_f32 v30, s[0:1], v34, v34, 1.0
	v_rcp_f32_e32 v39, v30
	v_div_fmas_f32 v26, v26, v28, v32
	v_div_fixup_f32 v35, v26, v35, 1.0
	v_pk_mul_f32 v[44:45], v[44:45], v[48:49]
	v_fma_f32 v26, -v30, v39, 1.0
	v_fmac_f32_e32 v39, v26, v39
	v_div_scale_f32 v26, vcc, 1.0, v34, 1.0
	v_mul_f32_e32 v28, v26, v39
	v_fma_f32 v32, -v30, v28, v26
	v_fmac_f32_e32 v28, v32, v39
	v_fma_f32 v26, -v30, v28, v26
	v_div_fmas_f32 v26, v26, v39, v28
	v_div_fixup_f32 v34, v26, v34, 1.0
	v_mov_b32_e32 v26, v29
	v_pk_add_f32 v[28:29], v[36:37], 1.0 op_sel_hi:[1,0]
	v_mov_b32_e32 v32, v169
	v_div_scale_f32 v30, s[0:1], v29, v29, 1.0
	v_rcp_f32_e32 v36, v30
	v_pk_mul_f32 v[26:27], v[26:27], v[38:39] op_sel_hi:[1,0]
	v_pk_mul_f32 v[34:35], v[44:45], v[34:35]
	v_mov_b32_e32 v33, v171
	v_pk_mul_f32 v[26:27], v[26:27], v[32:33]
	v_fma_f32 v31, -v30, v36, 1.0
	v_fmac_f32_e32 v36, v31, v36
	v_div_scale_f32 v31, vcc, 1.0, v29, 1.0
	v_mul_f32_e32 v32, v31, v36
	v_fma_f32 v33, -v30, v32, v31
	v_fmac_f32_e32 v32, v33, v36
	v_fma_f32 v30, -v30, v32, v31
	v_div_scale_f32 v31, s[0:1], v28, v28, 1.0
	v_rcp_f32_e32 v33, v31
	v_div_fmas_f32 v30, v30, v36, v32
	v_div_fixup_f32 v29, v30, v29, 1.0
	v_fma_f32 v30, -v31, v33, 1.0
	v_fmac_f32_e32 v33, v30, v33
	v_div_scale_f32 v30, vcc, 1.0, v28, 1.0
	v_mul_f32_e32 v32, v30, v33
	v_fma_f32 v36, -v31, v32, v30
	v_fmac_f32_e32 v32, v36, v33
	v_fma_f32 v30, -v31, v32, v30
	v_div_fmas_f32 v30, v30, v33, v32
	v_div_fixup_f32 v28, v30, v28, 1.0
	v_pk_mul_f32 v[26:27], v[26:27], v[28:29]
	v_and_b32_sdwa v28, v35, v142 dst_sel:DWORD dst_unused:UNUSED_PAD src0_sel:WORD_1 src1_sel:DWORD
	v_and_b32_sdwa v30, v27, v142 dst_sel:DWORD dst_unused:UNUSED_PAD src0_sel:WORD_1 src1_sel:DWORD
	v_and_b32_sdwa v31, v26, v142 dst_sel:DWORD dst_unused:UNUSED_PAD src0_sel:WORD_1 src1_sel:DWORD
	v_and_b32_sdwa v29, v34, v142 dst_sel:DWORD dst_unused:UNUSED_PAD src0_sel:WORD_1 src1_sel:DWORD
	v_add3_u32 v27, v27, v30, s25
	v_add3_u32 v26, v26, v31, s25
	v_add3_u32 v29, v34, v29, s25
	v_add3_u32 v28, v35, v28, s25
	v_and_b32_e32 v27, 0xffff0000, v27
	v_and_b32_e32 v26, 0xffff0000, v26
	v_or_b32_sdwa v27, v27, v28 dst_sel:DWORD dst_unused:UNUSED_PAD src0_sel:DWORD src1_sel:WORD_1
	v_or_b32_sdwa v26, v26, v29 dst_sel:DWORD dst_unused:UNUSED_PAD src0_sel:DWORD src1_sel:WORD_1
	global_store_dwordx2 v[0:1], v[26:27], off offset:32
	s_waitcnt vmcnt(6)
	v_and_b32_e32 v31, 0xffff0000, v208
	v_mul_f32_e32 v31, 0xbfb8aa3b, v31
	v_lshlrev_b32_e32 v30, 16, v208
	v_exp_f32_e32 v32, v31
	v_lshlrev_b32_e32 v31, 16, v209
	v_mul_f32_e32 v30, 0xbfb8aa3b, v30
	v_mul_f32_e32 v31, 0xbfb8aa3b, v31
	v_exp_f32_e32 v30, v30
	v_exp_f32_e32 v31, v31
	v_mov_b32_e32 v35, v22
	v_mov_b32_e32 v34, v24
	v_pk_mul_f32 v[34:35], v[34:35], v[38:39] op_sel_hi:[1,0]
	v_pk_add_f32 v[30:31], v[30:31], 1.0 op_sel_hi:[1,0]
	v_and_b32_e32 v33, 0xffff0000, v209
	v_div_scale_f32 v22, s[0:1], v31, v31, 1.0
	v_rcp_f32_e32 v24, v22
	v_mul_f32_e32 v33, 0xbfb8aa3b, v33
	v_exp_f32_e32 v33, v33
	v_mov_b32_e32 v36, v172
	v_fma_f32 v26, -v22, v24, 1.0
	v_fmac_f32_e32 v24, v26, v24
	v_div_scale_f32 v26, vcc, 1.0, v31, 1.0
	v_mov_b32_e32 v37, v174
	v_mul_f32_e32 v28, v26, v24
	v_pk_mul_f32 v[34:35], v[34:35], v[36:37]
	v_fma_f32 v36, -v22, v28, v26
	v_fmac_f32_e32 v28, v36, v24
	v_fma_f32 v22, -v22, v28, v26
	v_div_scale_f32 v26, s[0:1], v30, v30, 1.0
	v_rcp_f32_e32 v36, v26
	v_div_fmas_f32 v22, v22, v24, v28
	v_div_fixup_f32 v31, v22, v31, 1.0
	v_fma_f32 v22, -v26, v36, 1.0
	v_fmac_f32_e32 v36, v22, v36
	v_div_scale_f32 v22, vcc, 1.0, v30, 1.0
	v_mul_f32_e32 v24, v22, v36
	v_fma_f32 v28, -v26, v24, v22
	v_fmac_f32_e32 v24, v28, v36
	v_fma_f32 v22, -v26, v24, v22
	v_div_fmas_f32 v22, v22, v36, v24
	v_div_fixup_f32 v30, v22, v30, 1.0
	v_mov_b32_e32 v22, v25
	v_pk_add_f32 v[24:25], v[32:33], 1.0 op_sel_hi:[1,0]
	v_mov_b32_e32 v28, v173
	v_div_scale_f32 v26, s[0:1], v25, v25, 1.0
	v_rcp_f32_e32 v32, v26
	v_pk_mul_f32 v[22:23], v[22:23], v[38:39] op_sel_hi:[1,0]
	v_pk_mul_f32 v[30:31], v[34:35], v[30:31]
	v_mov_b32_e32 v29, v175
	v_pk_mul_f32 v[22:23], v[22:23], v[28:29]
	v_fma_f32 v27, -v26, v32, 1.0
	v_fmac_f32_e32 v32, v27, v32
	v_div_scale_f32 v27, vcc, 1.0, v25, 1.0
	v_mul_f32_e32 v28, v27, v32
	v_fma_f32 v29, -v26, v28, v27
	v_fmac_f32_e32 v28, v29, v32
	v_fma_f32 v26, -v26, v28, v27
	v_div_scale_f32 v27, s[0:1], v24, v24, 1.0
	v_rcp_f32_e32 v29, v27
	v_div_fmas_f32 v26, v26, v32, v28
	v_div_fixup_f32 v25, v26, v25, 1.0
	v_fma_f32 v26, -v27, v29, 1.0
	v_fmac_f32_e32 v29, v26, v29
	v_div_scale_f32 v26, vcc, 1.0, v24, 1.0
	v_mul_f32_e32 v28, v26, v29
	v_fma_f32 v32, -v27, v28, v26
	v_fmac_f32_e32 v28, v32, v29
	v_fma_f32 v26, -v27, v28, v26
	v_div_fmas_f32 v26, v26, v29, v28
	v_div_fixup_f32 v24, v26, v24, 1.0
	v_pk_mul_f32 v[22:23], v[22:23], v[24:25]
	v_and_b32_sdwa v24, v31, v142 dst_sel:DWORD dst_unused:UNUSED_PAD src0_sel:WORD_1 src1_sel:DWORD
	v_and_b32_sdwa v26, v23, v142 dst_sel:DWORD dst_unused:UNUSED_PAD src0_sel:WORD_1 src1_sel:DWORD
	v_and_b32_sdwa v27, v22, v142 dst_sel:DWORD dst_unused:UNUSED_PAD src0_sel:WORD_1 src1_sel:DWORD
	v_and_b32_sdwa v25, v30, v142 dst_sel:DWORD dst_unused:UNUSED_PAD src0_sel:WORD_1 src1_sel:DWORD
	v_add3_u32 v23, v23, v26, s25
	v_add3_u32 v22, v22, v27, s25
	v_add3_u32 v25, v30, v25, s25
	v_add3_u32 v24, v31, v24, s25
	v_and_b32_e32 v23, 0xffff0000, v23
	v_and_b32_e32 v22, 0xffff0000, v22
	v_or_b32_sdwa v23, v23, v24 dst_sel:DWORD dst_unused:UNUSED_PAD src0_sel:DWORD src1_sel:WORD_1
	v_or_b32_sdwa v22, v22, v25 dst_sel:DWORD dst_unused:UNUSED_PAD src0_sel:DWORD src1_sel:WORD_1
	global_store_dwordx2 v[0:1], v[22:23], off offset:48
	s_waitcnt vmcnt(6)
; __device__ __forceinline__ unsigned pk2(float lo, float hi) { return f2bf(lo) | (f2bf(hi) << 16); }
; __device__ __forceinline__ float bflo(unsigned w) { return __uint_as_float(w << 16); }
; __device__ __forceinline__ float bfhi(unsigned w) { return __uint_as_float(w & 0xffff0000u); }
; __device__ __forceinline__ float sigmoidf_(float x) { return 1.0f / (1.0f + __expf(-x)); }
; __device__ __forceinline__ void mlstm_stage_c(LAS unsigned char* lds, const bf16_t* QKO, const bf16_t* KVT, const float* G, const float* gbias, const bf16_t* DC, const float* DN, ...
;     ...
;         for (int tb = 0; tb < 2; ++tb) { const int t = tb * 32 + r32; float tot = 0.f;
; #pragma unroll
;             for (int w = 0; w < 8; ++w) tot += sSsq[w * 64 + t];
;             const float rstd = 1.0f / sqrtf(tot * (1.0f / 512.0f) + EPS);
; #pragma unroll
;             for (int vb = 0; vb < 2; ++vb)
; #pragma unroll
;                 for (int gq = 0; gq < 4; ++gq) { const int v0 = wave * 64 + vb * 32 + 8 * gq + 4 * hi;
;                     const u32x2 ow = *(const u32x2*)(QKO + (size_t)(t0 + t) * 4096 + 2048 + h * 512 + v0);
;                     const f32x4 gn = *(const f32x4*)(hnorm + h * 512 + v0);
;                     const float o0 = acc[vb][tb][4 * gq] * rstd * gn.x * sigmoidf_(bflo(ow.x)), o1 = acc[vb][tb][4 * gq + 1] * rstd * gn.y * sigmoidf_(bfhi(ow.x));
;                     const float o2 = acc[vb][tb][4 * gq + 2] * rstd * gn.z * sigmoidf_(bflo(ow.y)), o3 = acc[vb][tb][4 * gq + 3] * rstd * gn.w * sigmoidf_(bfhi(ow.y));
;                     u32x2 w; w.x = pk2(o0, o1); w.y = pk2(o2, o3);
;                     *(u32x2*)(HG + (size_t)(t0 + t) * 2048 + h * 512 + v0) = w; } }
	v_lshlrev_b32_e32 v26, 16, v210
	v_lshlrev_b32_e32 v27, 16, v211
	v_mul_f32_e32 v26, 0xbfb8aa3b, v26
	v_mul_f32_e32 v27, 0xbfb8aa3b, v27
	v_exp_f32_e32 v26, v26
	v_exp_f32_e32 v27, v27
	v_mov_b32_e32 v29, v18
	v_mov_b32_e32 v28, v20
	v_pk_mul_f32 v[28:29], v[28:29], v[38:39] op_sel_hi:[1,0]
	v_pk_add_f32 v[26:27], v[26:27], 1.0 op_sel_hi:[1,0]
	v_and_b32_e32 v2, 0xffff0000, v210
	v_div_scale_f32 v18, s[0:1], v27, v27, 1.0
	v_rcp_f32_e32 v20, v18
	v_and_b32_e32 v3, 0xffff0000, v211
	v_mul_f32_e32 v2, 0xbfb8aa3b, v2
	v_mul_f32_e32 v3, 0xbfb8aa3b, v3
	v_exp_f32_e32 v2, v2
	v_exp_f32_e32 v3, v3
	v_mov_b32_e32 v30, v176
	v_fma_f32 v22, -v18, v20, 1.0
	v_fmac_f32_e32 v20, v22, v20
	v_div_scale_f32 v22, vcc, 1.0, v27, 1.0
	v_mov_b32_e32 v31, v178
	v_mul_f32_e32 v24, v22, v20
	v_pk_mul_f32 v[28:29], v[28:29], v[30:31]
	v_fma_f32 v30, -v18, v24, v22
	v_fmac_f32_e32 v24, v30, v20
	v_fma_f32 v18, -v18, v24, v22
	v_div_scale_f32 v22, s[0:1], v26, v26, 1.0
	v_rcp_f32_e32 v30, v22
	v_div_fmas_f32 v18, v18, v20, v24
	v_div_fixup_f32 v27, v18, v27, 1.0
	v_pk_add_f32 v[2:3], v[2:3], 1.0 op_sel_hi:[1,0]
	v_fma_f32 v18, -v22, v30, 1.0
	v_fmac_f32_e32 v30, v18, v30
	v_div_scale_f32 v18, vcc, 1.0, v26, 1.0
	v_mul_f32_e32 v20, v18, v30
	v_fma_f32 v24, -v22, v20, v18
	v_fmac_f32_e32 v20, v24, v30
	v_fma_f32 v18, -v22, v20, v18
	v_div_fmas_f32 v18, v18, v30, v20
	v_div_scale_f32 v20, s[0:1], v3, v3, 1.0
	v_div_fixup_f32 v26, v18, v26, 1.0
	v_mov_b32_e32 v18, v21
	v_rcp_f32_e32 v21, v20
	v_pk_mul_f32 v[18:19], v[18:19], v[38:39] op_sel_hi:[1,0]
	v_mov_b32_e32 v24, v177
	v_mov_b32_e32 v25, v179
	v_pk_mul_f32 v[18:19], v[18:19], v[24:25]
	v_fma_f32 v22, -v20, v21, 1.0
	v_fmac_f32_e32 v21, v22, v21
	v_div_scale_f32 v22, vcc, 1.0, v3, 1.0
	v_mul_f32_e32 v23, v22, v21
	v_fma_f32 v24, -v20, v23, v22
	v_fmac_f32_e32 v23, v24, v21
	v_div_scale_f32 v24, s[0:1], v2, v2, 1.0
	v_rcp_f32_e32 v25, v24
	v_fma_f32 v20, -v20, v23, v22
	v_div_fmas_f32 v20, v20, v21, v23
	v_div_fixup_f32 v3, v20, v3, 1.0
	v_fma_f32 v20, -v24, v25, 1.0
	v_fmac_f32_e32 v25, v20, v25
	v_div_scale_f32 v20, vcc, 1.0, v2, 1.0
	v_mul_f32_e32 v21, v20, v25
	v_fma_f32 v22, -v24, v21, v20
	v_fmac_f32_e32 v21, v22, v25
	v_fma_f32 v20, -v24, v21, v20
	v_div_fmas_f32 v20, v20, v25, v21
	v_div_fixup_f32 v2, v20, v2, 1.0
	v_pk_mul_f32 v[2:3], v[18:19], v[2:3]
	v_pk_mul_f32 v[26:27], v[28:29], v[26:27]
	v_and_b32_sdwa v20, v3, v142 dst_sel:DWORD dst_unused:UNUSED_PAD src0_sel:WORD_1 src1_sel:DWORD
	v_and_b32_sdwa v21, v2, v142 dst_sel:DWORD dst_unused:UNUSED_PAD src0_sel:WORD_1 src1_sel:DWORD
	v_and_b32_sdwa v18, v27, v142 dst_sel:DWORD dst_unused:UNUSED_PAD src0_sel:WORD_1 src1_sel:DWORD
	v_and_b32_sdwa v19, v26, v142 dst_sel:DWORD dst_unused:UNUSED_PAD src0_sel:WORD_1 src1_sel:DWORD
	v_add3_u32 v3, v3, v20, s25
	v_add3_u32 v2, v2, v21, s25
	v_add3_u32 v19, v26, v19, s25
	v_add3_u32 v18, v27, v18, s25
	v_and_b32_e32 v3, 0xffff0000, v3
	v_and_b32_e32 v2, 0xffff0000, v2
	v_or_b32_sdwa v3, v3, v18 dst_sel:DWORD dst_unused:UNUSED_PAD src0_sel:DWORD src1_sel:WORD_1
	v_or_b32_sdwa v2, v2, v19 dst_sel:DWORD dst_unused:UNUSED_PAD src0_sel:DWORD src1_sel:WORD_1
	global_store_dwordx2 v[0:1], v[2:3], off offset:64
	s_nop 0
	v_mov_b32_e32 v27, v6
	v_mov_b32_e32 v26, v16
	v_pk_mul_f32 v[26:27], v[26:27], v[38:39] op_sel_hi:[1,0]
	s_waitcnt vmcnt(6)
	v_lshlrev_b32_e32 v24, 16, v212
	v_lshlrev_b32_e32 v25, 16, v213
	v_mul_f32_e32 v24, 0xbfb8aa3b, v24
	v_mul_f32_e32 v25, 0xbfb8aa3b, v25
	v_exp_f32_e32 v24, v24
	v_exp_f32_e32 v25, v25
	v_and_b32_e32 v22, 0xffff0000, v212
	v_and_b32_e32 v23, 0xffff0000, v213
	v_mul_f32_e32 v22, 0xbfb8aa3b, v22
	v_pk_add_f32 v[24:25], v[24:25], 1.0 op_sel_hi:[1,0]
	v_mul_f32_e32 v23, 0xbfb8aa3b, v23
	v_div_scale_f32 v6, s[0:1], v25, v25, 1.0
	v_rcp_f32_e32 v16, v6
	v_exp_f32_e32 v22, v22
	v_exp_f32_e32 v23, v23
	v_mov_b32_e32 v28, v184
	v_fma_f32 v18, -v6, v16, 1.0
	v_fmac_f32_e32 v16, v18, v16
	v_div_scale_f32 v18, vcc, 1.0, v25, 1.0
	v_mov_b32_e32 v29, v186
	v_mul_f32_e32 v20, v18, v16
	v_pk_mul_f32 v[26:27], v[26:27], v[28:29]
	v_fma_f32 v28, -v6, v20, v18
	v_fmac_f32_e32 v20, v28, v16
	v_fma_f32 v6, -v6, v20, v18
	v_div_scale_f32 v18, s[0:1], v24, v24, 1.0
	v_rcp_f32_e32 v28, v18
	v_div_fmas_f32 v6, v6, v16, v20
	v_div_fixup_f32 v25, v6, v25, 1.0
	v_fma_f32 v6, -v18, v28, 1.0
	v_fmac_f32_e32 v28, v6, v28
	v_div_scale_f32 v6, vcc, 1.0, v24, 1.0
	v_mul_f32_e32 v16, v6, v28
	v_fma_f32 v20, -v18, v16, v6
	v_fmac_f32_e32 v16, v20, v28
	v_fma_f32 v6, -v18, v16, v6
	v_div_fmas_f32 v6, v6, v28, v16
	v_div_fixup_f32 v24, v6, v24, 1.0
	v_mov_b32_e32 v6, v17
	v_pk_add_f32 v[16:17], v[22:23], 1.0 op_sel_hi:[1,0]
	v_mov_b32_e32 v20, v185
	v_div_scale_f32 v18, s[0:1], v17, v17, 1.0
	v_rcp_f32_e32 v22, v18
	v_pk_mul_f32 v[6:7], v[6:7], v[38:39] op_sel_hi:[1,0]
	v_pk_mul_f32 v[24:25], v[26:27], v[24:25]
	v_mov_b32_e32 v21, v187
	v_pk_mul_f32 v[6:7], v[6:7], v[20:21]
	v_fma_f32 v19, -v18, v22, 1.0
	v_fmac_f32_e32 v22, v19, v22
	v_div_scale_f32 v19, vcc, 1.0, v17, 1.0
	v_mul_f32_e32 v20, v19, v22
	v_fma_f32 v21, -v18, v20, v19
	v_fmac_f32_e32 v20, v21, v22
	v_fma_f32 v18, -v18, v20, v19
	v_div_scale_f32 v19, s[0:1], v16, v16, 1.0
	v_rcp_f32_e32 v21, v19
	v_div_fmas_f32 v18, v18, v22, v20
	v_div_fixup_f32 v17, v18, v17, 1.0
	v_fma_f32 v18, -v19, v21, 1.0
	v_fmac_f32_e32 v21, v18, v21
	v_div_scale_f32 v18, vcc, 1.0, v16, 1.0
	v_mul_f32_e32 v20, v18, v21
	v_fma_f32 v22, -v19, v20, v18
	v_fmac_f32_e32 v20, v22, v21
	v_fma_f32 v18, -v19, v20, v18
	v_div_fmas_f32 v18, v18, v21, v20
	v_div_fixup_f32 v16, v18, v16, 1.0
	v_pk_mul_f32 v[6:7], v[6:7], v[16:17]
	v_and_b32_sdwa v16, v25, v142 dst_sel:DWORD dst_unused:UNUSED_PAD src0_sel:WORD_1 src1_sel:DWORD
	v_and_b32_sdwa v18, v7, v142 dst_sel:DWORD dst_unused:UNUSED_PAD src0_sel:WORD_1 src1_sel:DWORD
	v_and_b32_sdwa v19, v6, v142 dst_sel:DWORD dst_unused:UNUSED_PAD src0_sel:WORD_1 src1_sel:DWORD
	v_and_b32_sdwa v17, v24, v142 dst_sel:DWORD dst_unused:UNUSED_PAD src0_sel:WORD_1 src1_sel:DWORD
	v_add3_u32 v7, v7, v18, s25
	v_add3_u32 v6, v6, v19, s25
	v_add3_u32 v17, v24, v17, s25
	v_add3_u32 v16, v25, v16, s25
	v_and_b32_e32 v7, 0xffff0000, v7
	v_and_b32_e32 v6, 0xffff0000, v6
	v_or_b32_sdwa v7, v7, v16 dst_sel:DWORD dst_unused:UNUSED_PAD src0_sel:DWORD src1_sel:WORD_1
	v_or_b32_sdwa v6, v6, v17 dst_sel:DWORD dst_unused:UNUSED_PAD src0_sel:DWORD src1_sel:WORD_1
	global_store_dwordx2 v[0:1], v[6:7], off offset:80
	s_waitcnt vmcnt(6)
; __device__ __forceinline__ unsigned pk2(float lo, float hi) { return f2bf(lo) | (f2bf(hi) << 16); }
; __device__ __forceinline__ float bflo(unsigned w) { return __uint_as_float(w << 16); }
; __device__ __forceinline__ float bfhi(unsigned w) { return __uint_as_float(w & 0xffff0000u); }
; __device__ __forceinline__ float sigmoidf_(float x) { return 1.0f / (1.0f + __expf(-x)); }
; __device__ __forceinline__ void mlstm_stage_c(LAS unsigned char* lds, const bf16_t* QKO, const bf16_t* KVT, const float* G, const float* gbias, const bf16_t* DC, const float* DN, ...
;     ...
;         for (int tb = 0; tb < 2; ++tb) { const int t = tb * 32 + r32; float tot = 0.f;
; #pragma unroll
;             for (int w = 0; w < 8; ++w) tot += sSsq[w * 64 + t];
;             const float rstd = 1.0f / sqrtf(tot * (1.0f / 512.0f) + EPS);
; #pragma unroll
;             for (int vb = 0; vb < 2; ++vb)
; #pragma unroll
;                 for (int gq = 0; gq < 4; ++gq) { const int v0 = wave * 64 + vb * 32 + 8 * gq + 4 * hi;
;                     const u32x2 ow = *(const u32x2*)(QKO + (size_t)(t0 + t) * 4096 + 2048 + h * 512 + v0);
;                     const f32x4 gn = *(const f32x4*)(hnorm + h * 512 + v0);
;                     const float o0 = acc[vb][tb][4 * gq] * rstd * gn.x * sigmoidf_(bflo(ow.x)), o1 = acc[vb][tb][4 * gq + 1] * rstd * gn.y * sigmoidf_(bfhi(ow.x));
;                     const float o2 = acc[vb][tb][4 * gq + 2] * rstd * gn.z * sigmoidf_(bflo(ow.y)), o3 = acc[vb][tb][4 * gq + 3] * rstd * gn.w * sigmoidf_(bfhi(ow.y));
;                     u32x2 w; w.x = pk2(o0, o1); w.y = pk2(o2, o3);
;                     *(u32x2*)(HG + (size_t)(t0 + t) * 2048 + h * 512 + v0) = w; } }
	v_lshlrev_b32_e32 v6, 16, v214
	v_lshlrev_b32_e32 v7, 16, v215
	v_mul_f32_e32 v6, 0xbfb8aa3b, v6
	v_mul_f32_e32 v7, 0xbfb8aa3b, v7
	v_exp_f32_e32 v6, v6
	v_exp_f32_e32 v7, v7
	v_mov_b32_e32 v20, v8
	v_mov_b32_e32 v21, v10
	v_pk_mul_f32 v[20:21], v[20:21], v[38:39] op_sel_hi:[1,0]
	v_pk_add_f32 v[6:7], v[6:7], 1.0 op_sel_hi:[1,0]
	v_and_b32_e32 v2, 0xffff0000, v214
	v_div_scale_f32 v8, s[0:1], v7, v7, 1.0
	v_rcp_f32_e32 v10, v8
	v_and_b32_e32 v3, 0xffff0000, v215
	v_mul_f32_e32 v2, 0xbfb8aa3b, v2
	v_mul_f32_e32 v3, 0xbfb8aa3b, v3
	v_exp_f32_e32 v2, v2
	v_exp_f32_e32 v3, v3
	v_mov_b32_e32 v22, v188
	v_fma_f32 v16, -v8, v10, 1.0
	v_fmac_f32_e32 v10, v16, v10
	v_div_scale_f32 v16, vcc, 1.0, v7, 1.0
	v_mov_b32_e32 v23, v190
	v_mul_f32_e32 v18, v16, v10
	v_pk_mul_f32 v[20:21], v[20:21], v[22:23]
	v_fma_f32 v22, -v8, v18, v16
	v_fmac_f32_e32 v18, v22, v10
	v_fma_f32 v8, -v8, v18, v16
	v_div_scale_f32 v16, s[0:1], v6, v6, 1.0
	v_rcp_f32_e32 v22, v16
	v_div_fmas_f32 v8, v8, v10, v18
	v_div_fixup_f32 v7, v8, v7, 1.0
	v_pk_add_f32 v[2:3], v[2:3], 1.0 op_sel_hi:[1,0]
	v_fma_f32 v8, -v16, v22, 1.0
	v_fmac_f32_e32 v22, v8, v22
	v_div_scale_f32 v8, vcc, 1.0, v6, 1.0
	v_mul_f32_e32 v10, v8, v22
	v_fma_f32 v18, -v16, v10, v8
	v_fmac_f32_e32 v10, v18, v22
	v_fma_f32 v8, -v16, v10, v8
	v_div_fmas_f32 v8, v8, v22, v10
	v_div_fixup_f32 v6, v8, v6, 1.0
	v_div_scale_f32 v16, s[0:1], v3, v3, 1.0
	v_pk_mul_f32 v[6:7], v[20:21], v[6:7]
	v_rcp_f32_e32 v20, v16
	v_mov_b32_e32 v10, v9
	v_pk_mul_f32 v[8:9], v[10:11], v[38:39] op_sel_hi:[1,0]
	v_mov_b32_e32 v18, v189
	v_fma_f32 v10, -v16, v20, 1.0
	v_fmac_f32_e32 v20, v10, v20
	v_div_scale_f32 v10, vcc, 1.0, v3, 1.0
	v_mul_f32_e32 v11, v10, v20
	v_fma_f32 v17, -v16, v11, v10
	v_fmac_f32_e32 v11, v17, v20
	v_fma_f32 v10, -v16, v11, v10
	v_div_scale_f32 v16, s[0:1], v2, v2, 1.0
	v_rcp_f32_e32 v17, v16
	v_div_fmas_f32 v10, v10, v20, v11
	v_div_fixup_f32 v3, v10, v3, 1.0
	v_mov_b32_e32 v19, v191
	v_pk_mul_f32 v[8:9], v[8:9], v[18:19]
	v_fma_f32 v10, -v16, v17, 1.0
	v_fmac_f32_e32 v17, v10, v17
	v_div_scale_f32 v10, vcc, 1.0, v2, 1.0
	v_mul_f32_e32 v11, v10, v17
	v_fma_f32 v18, -v16, v11, v10
	v_fmac_f32_e32 v11, v18, v17
	v_fma_f32 v10, -v16, v11, v10
	v_div_fmas_f32 v10, v10, v17, v11
	v_div_fixup_f32 v2, v10, v2, 1.0
	v_pk_mul_f32 v[2:3], v[8:9], v[2:3]
	v_and_b32_sdwa v8, v7, v142 dst_sel:DWORD dst_unused:UNUSED_PAD src0_sel:WORD_1 src1_sel:DWORD
	v_and_b32_sdwa v9, v6, v142 dst_sel:DWORD dst_unused:UNUSED_PAD src0_sel:WORD_1 src1_sel:DWORD
	v_add3_u32 v6, v6, v9, s25
	v_add3_u32 v7, v7, v8, s25
	v_and_b32_sdwa v8, v3, v142 dst_sel:DWORD dst_unused:UNUSED_PAD src0_sel:WORD_1 src1_sel:DWORD
	v_and_b32_sdwa v9, v2, v142 dst_sel:DWORD dst_unused:UNUSED_PAD src0_sel:WORD_1 src1_sel:DWORD
	v_add3_u32 v3, v3, v8, s25
	v_add3_u32 v2, v2, v9, s25
	v_and_b32_e32 v3, 0xffff0000, v3
	v_and_b32_e32 v2, 0xffff0000, v2
	v_or_b32_sdwa v3, v3, v7 dst_sel:DWORD dst_unused:UNUSED_PAD src0_sel:DWORD src1_sel:WORD_1
	v_or_b32_sdwa v2, v2, v6 dst_sel:DWORD dst_unused:UNUSED_PAD src0_sel:DWORD src1_sel:WORD_1
	global_store_dwordx2 v[0:1], v[2:3], off offset:96
	v_and_b32_e32 v7, 0xffff0000, v198
	v_mul_f32_e32 v7, 0xbfb8aa3b, v7
	v_lshlrev_b32_e32 v6, 16, v198
	v_exp_f32_e32 v8, v7
	v_lshlrev_b32_e32 v7, 16, v199
	v_mul_f32_e32 v6, 0xbfb8aa3b, v6
	v_mul_f32_e32 v7, 0xbfb8aa3b, v7
	v_exp_f32_e32 v6, v6
	v_exp_f32_e32 v7, v7
	v_mov_b32_e32 v10, v12
	v_mov_b32_e32 v11, v14
	v_pk_mul_f32 v[10:11], v[10:11], v[38:39] op_sel_hi:[1,0]
	v_pk_add_f32 v[6:7], v[6:7], 1.0 op_sel_hi:[1,0]
	v_and_b32_e32 v9, 0xffff0000, v199
	v_div_scale_f32 v12, s[0:1], v7, v7, 1.0
	v_rcp_f32_e32 v14, v12
	v_mul_f32_e32 v9, 0xbfb8aa3b, v9
	v_exp_f32_e32 v9, v9
	v_mov_b32_e32 v16, v192
	v_fma_f32 v2, -v12, v14, 1.0
	v_fmac_f32_e32 v14, v2, v14
	v_div_scale_f32 v2, vcc, 1.0, v7, 1.0
	v_mov_b32_e32 v17, v194
	v_mul_f32_e32 v4, v2, v14
	v_pk_mul_f32 v[10:11], v[10:11], v[16:17]
	v_fma_f32 v16, -v12, v4, v2
	v_fmac_f32_e32 v4, v16, v14
	v_fma_f32 v2, -v12, v4, v2
	v_div_scale_f32 v12, s[0:1], v6, v6, 1.0
	v_rcp_f32_e32 v16, v12
	v_div_fmas_f32 v2, v2, v14, v4
	v_div_fixup_f32 v7, v2, v7, 1.0
	v_pk_add_f32 v[8:9], v[8:9], 1.0 op_sel_hi:[1,0]
	v_fma_f32 v2, -v12, v16, 1.0
	v_fmac_f32_e32 v16, v2, v16
	v_div_scale_f32 v2, vcc, 1.0, v6, 1.0
	v_mul_f32_e32 v4, v2, v16
	v_fma_f32 v14, -v12, v4, v2
	v_fmac_f32_e32 v4, v14, v16
	v_fma_f32 v2, -v12, v4, v2
	v_div_scale_f32 v12, s[0:1], v9, v9, 1.0
	v_mov_b32_e32 v14, v13
	v_rcp_f32_e32 v13, v12
	v_div_fmas_f32 v2, v2, v16, v4
	v_div_fixup_f32 v6, v2, v6, 1.0
	v_pk_mul_f32 v[6:7], v[10:11], v[6:7]
	v_pk_mul_f32 v[10:11], v[14:15], v[38:39] op_sel_hi:[1,0]
	v_mov_b32_e32 v4, v193
	v_mov_b32_e32 v5, v195
	v_pk_mul_f32 v[2:3], v[10:11], v[4:5]
	v_fma_f32 v4, -v12, v13, 1.0
	v_fmac_f32_e32 v13, v4, v13
	v_div_scale_f32 v4, vcc, 1.0, v9, 1.0
	v_mul_f32_e32 v5, v4, v13
	v_fma_f32 v10, -v12, v5, v4
	v_fmac_f32_e32 v5, v10, v13
	v_div_scale_f32 v10, s[0:1], v8, v8, 1.0
	v_rcp_f32_e32 v11, v10
	v_fma_f32 v4, -v12, v5, v4
	v_div_fmas_f32 v4, v4, v13, v5
	v_div_fixup_f32 v5, v4, v9, 1.0
	v_fma_f32 v4, -v10, v11, 1.0
	v_fmac_f32_e32 v11, v4, v11
	v_div_scale_f32 v4, vcc, 1.0, v8, 1.0
	v_mul_f32_e32 v9, v4, v11
	v_fma_f32 v12, -v10, v9, v4
	v_fmac_f32_e32 v9, v12, v11
	v_fma_f32 v4, -v10, v9, v4
	v_div_fmas_f32 v4, v4, v11, v9
	v_div_fixup_f32 v4, v4, v8, 1.0
	v_readlane_b32 s0, v249, 62
	v_pk_mul_f32 v[2:3], v[2:3], v[4:5]
	v_and_b32_sdwa v4, v7, v142 dst_sel:DWORD dst_unused:UNUSED_PAD src0_sel:WORD_1 src1_sel:DWORD
	v_and_b32_sdwa v5, v6, v142 dst_sel:DWORD dst_unused:UNUSED_PAD src0_sel:WORD_1 src1_sel:DWORD
	v_readlane_b32 s1, v249, 63
	s_add_u32 s36, s36, s0
	v_add3_u32 v5, v6, v5, s25
	v_add3_u32 v4, v7, v4, s25
	v_and_b32_sdwa v6, v3, v142 dst_sel:DWORD dst_unused:UNUSED_PAD src0_sel:WORD_1 src1_sel:DWORD
	v_and_b32_sdwa v7, v2, v142 dst_sel:DWORD dst_unused:UNUSED_PAD src0_sel:WORD_1 src1_sel:DWORD
	s_addc_u32 s37, s37, s1
	v_add3_u32 v3, v3, v6, s25
	v_add3_u32 v2, v2, v7, s25
	s_add_u32 s76, s76, s74
	v_and_b32_e32 v3, 0xffff0000, v3
	v_and_b32_e32 v2, 0xffff0000, v2
	s_addc_u32 s77, s77, s75
	s_add_i32 s55, s55, s87
	v_or_b32_sdwa v3, v3, v4 dst_sel:DWORD dst_unused:UNUSED_PAD src0_sel:DWORD src1_sel:WORD_1
	v_or_b32_sdwa v2, v2, v5 dst_sel:DWORD dst_unused:UNUSED_PAD src0_sel:DWORD src1_sel:WORD_1
	s_cmpk_lt_i32 s36, 0x400
	global_store_dwordx2 v[0:1], v[2:3], off offset:112
	s_barrier
	s_cbranch_scc0 .LBB0_826
